# EpiBf16 epilogue: 8 serialized rowss atomic loads hoisted to epilogue top with counted vmcnt waits
# baseline (speedup 1.0000x reference)
; __device__ __forceinline__ unsigned cvt_pk_bf16(float lo, float hi) { unsigned r; asm volatile("v_cvt_pk_bf16_f32 %0, %1, %2" : "=v"(r) : "v"(lo), "v"(hi)); return r; }
;     __device__ __forceinline__ void operator()(const f32x4 (&acc)[2][2][4][2], const Unit& u, int wr, int wc, int fr, int fq) const {
;     ...
;             for (int m = 0; m < 4; ++m) { bf16_t* rowp = O + (size_t)(row0 + ai * HALF + m * 16) * ldc + col0;
;                 const float rs = rowss ? sc * (1.0f / sqrtf((float)__hip_atomic_load(rowss + row0 + ai * HALF + m * 16, __ATOMIC_RELAXED, __HIP_MEMORY_SCOPE_AGENT) * (1.0f / (2048.0f * 1048576.0f)) + 1e-6f)) : sc;
; #pragma unroll
;                 for (int bj = 0; bj < 2; ++bj) { f32x4 v0 = acc[ai][bj][m][0] * rs, v1 = acc[ai][bj][m][1] * rs;
;                     if (ACT == 1) {
; #pragma unroll
;                         for (int e = 0; e < 4; ++e) { float a = v0[e] > 0.f ? v0[e] : 0.f; v0[e] = a * a; float b = v1[e] > 0.f ? v1[e] : 0.f; v1[e] = b * b; } }
;                     u32x4 w; w.x = cvt_pk_bf16(v0[0], v0[1]); w.y = cvt_pk_bf16(v0[2], v0[3]); w.z = cvt_pk_bf16(v1[0], v1[1]); w.w = cvt_pk_bf16(v1[2], v1[3]);
;                     *(u32x4*)(rowp + bj * HALF) = w; } }
.LBB0_136:
	v_lshl_add_u32 v138, s39, 8, v145
	v_ashrrev_i32_e32 v139, 31, v138
	v_cndmask_b32_e64 v140, 0, 1, s[8:9]
	v_mov_b32_e32 v144, 1.0
	v_cmp_ne_u32_e64 s[4:5], 1, v140
	s_andn2_b64 vcc, exec, s[8:9]
	v_lshl_add_u64 v[140:141], v[138:139], 3, s[10:11]
	v_mov_b32_e32 v146, 1.0
	s_cbranch_vccnz .LBB0_138
	global_load_dwordx2 v[156:157], v[140:141], off sc1
	global_load_dwordx2 v[158:159], v[140:141], off offset:128 sc1
	global_load_dwordx2 v[160:161], v[140:141], off offset:256 sc1
	global_load_dwordx2 v[162:163], v[140:141], off offset:384 sc1
	global_load_dwordx2 v[164:165], v[140:141], off offset:1024 sc1
	global_load_dwordx2 v[166:167], v[140:141], off offset:1152 sc1
	global_load_dwordx2 v[168:169], v[140:141], off offset:1280 sc1
	global_load_dwordx2 v[170:171], v[140:141], off offset:1408 sc1
	s_waitcnt vmcnt(7)
	v_mov_b32_e32 v142, v156
	v_mov_b32_e32 v143, v157
	v_ffbh_u32_e32 v139, v143
	v_min_u32_e32 v139, 32, v139
	v_lshlrev_b64 v[142:143], v139, v[142:143]
	v_min_u32_e32 v142, 1, v142
	v_or_b32_e32 v142, v143, v142
	v_cvt_f32_u32_e32 v142, v142
	v_sub_u32_e32 v139, 32, v139
	v_ldexp_f32 v139, v142, v139
	v_fmamk_f32 v139, v139, 0x30000000, v208
	v_mul_f32_e32 v142, 0x4f800000, v139
	v_cmp_gt_f32_e32 vcc, s33, v139
	s_nop 1
	v_cndmask_b32_e32 v139, v139, v142, vcc
	v_sqrt_f32_e32 v142, v139
	s_nop 0
	v_add_u32_e32 v143, -1, v142
	v_add_u32_e32 v146, 1, v142
	v_fma_f32 v150, -v143, v142, v139
	v_fma_f32 v151, -v146, v142, v139
	v_cmp_ge_f32_e64 s[6:7], 0, v150
	s_nop 1
	v_cndmask_b32_e64 v142, v142, v143, s[6:7]
	v_cmp_lt_f32_e64 s[6:7], 0, v151
	s_nop 1
	v_cndmask_b32_e64 v142, v142, v146, s[6:7]
	v_mul_f32_e32 v143, 0x37800000, v142
	v_cndmask_b32_e32 v142, v142, v143, vcc
	v_cmp_class_f32_e32 vcc, v139, v209
	s_nop 1
	v_cndmask_b32_e32 v139, v142, v139, vcc
	v_div_scale_f32 v142, s[6:7], v139, v139, 1.0
	v_rcp_f32_e32 v143, v142
	v_div_scale_f32 v146, vcc, 1.0, v139, 1.0
	v_fma_f32 v150, -v142, v143, 1.0
	v_fmac_f32_e32 v143, v150, v143
	v_mul_f32_e32 v150, v146, v143
	v_fma_f32 v151, -v142, v150, v146
	v_fmac_f32_e32 v150, v151, v143
	v_fma_f32 v142, -v142, v150, v146
	v_div_fmas_f32 v142, v142, v143, v150
	v_div_fixup_f32 v146, v142, v139, 1.0
.LBB0_138:
	v_lshl_or_b32 v142, s38, 8, v148
	v_mov_b64_e32 v[150:151], s[78:79]
	v_ashrrev_i32_e32 v143, 31, v142
	v_mad_i64_i32 v[150:151], s[6:7], v138, s91, v[150:151]
	v_lshl_add_u64 v[150:151], v[142:143], 1, v[150:151]
	v_pk_mul_f32 v[126:127], v[126:127], v[146:147] op_sel_hi:[1,0]
	v_pk_mul_f32 v[124:125], v[124:125], v[146:147] op_sel_hi:[1,0]
	v_pk_mul_f32 v[152:153], v[122:123], v[146:147] op_sel_hi:[1,0]
	v_pk_mul_f32 v[122:123], v[120:121], v[146:147] op_sel_hi:[1,0]
	v_cvt_pk_bf16_f32 v120, v124, v125
	v_cvt_pk_bf16_f32 v121, v126, v127
	s_and_b64 vcc, exec, s[4:5]
	v_cvt_pk_bf16_f32 v122, v122, v123
	v_cvt_pk_bf16_f32 v123, v152, v153
	global_store_dwordx4 v[150:151], v[120:123], off
	v_pk_mul_f32 v[118:119], v[118:119], v[146:147] op_sel_hi:[1,0]
	v_pk_mul_f32 v[116:117], v[116:117], v[146:147] op_sel_hi:[1,0]
	v_pk_mul_f32 v[120:121], v[114:115], v[146:147] op_sel_hi:[1,0]
	v_pk_mul_f32 v[114:115], v[112:113], v[146:147] op_sel_hi:[1,0]
	v_cvt_pk_bf16_f32 v112, v116, v117
	v_cvt_pk_bf16_f32 v113, v118, v119
	s_nop 0
	v_cvt_pk_bf16_f32 v114, v114, v115
	v_cvt_pk_bf16_f32 v115, v120, v121
	global_store_dwordx4 v[150:151], v[112:115], off offset:256
	s_cbranch_vccnz .LBB0_140
	s_waitcnt vmcnt(8)
	s_nop 0
	v_mov_b32_e32 v112, v158
	v_mov_b32_e32 v113, v159
	v_ffbh_u32_e32 v114, v113
	v_min_u32_e32 v114, 32, v114
	v_lshlrev_b64 v[112:113], v114, v[112:113]
	v_min_u32_e32 v112, 1, v112
	v_or_b32_e32 v112, v113, v112
	v_cvt_f32_u32_e32 v112, v112
	v_sub_u32_e32 v113, 32, v114
	v_ldexp_f32 v112, v112, v113
	v_fmamk_f32 v112, v112, 0x30000000, v208
	v_mul_f32_e32 v113, 0x4f800000, v112
	v_cmp_gt_f32_e32 vcc, s33, v112
	s_nop 1
	v_cndmask_b32_e32 v112, v112, v113, vcc
	v_sqrt_f32_e32 v113, v112
	s_nop 0
	v_add_u32_e32 v114, -1, v113
	v_add_u32_e32 v115, 1, v113
	v_fma_f32 v116, -v114, v113, v112
	v_fma_f32 v117, -v115, v113, v112
	v_cmp_ge_f32_e64 s[6:7], 0, v116
	s_nop 1
	v_cndmask_b32_e64 v113, v113, v114, s[6:7]
	v_cmp_lt_f32_e64 s[6:7], 0, v117
	s_nop 1
	v_cndmask_b32_e64 v113, v113, v115, s[6:7]
	v_mul_f32_e32 v114, 0x37800000, v113
	v_cndmask_b32_e32 v113, v113, v114, vcc
	v_cmp_class_f32_e32 vcc, v112, v209
	s_nop 1
	v_cndmask_b32_e32 v112, v113, v112, vcc
	v_div_scale_f32 v113, s[6:7], v112, v112, 1.0
	v_rcp_f32_e32 v114, v113
	v_div_scale_f32 v115, vcc, 1.0, v112, 1.0
	v_fma_f32 v116, -v113, v114, 1.0
	v_fmac_f32_e32 v114, v116, v114
	v_mul_f32_e32 v116, v115, v114
	v_fma_f32 v117, -v113, v116, v115
	v_fmac_f32_e32 v116, v117, v114
	v_fma_f32 v113, -v113, v116, v115
	v_div_fmas_f32 v113, v113, v114, v116
	v_div_fixup_f32 v144, v113, v112, 1.0
; __device__ __forceinline__ unsigned cvt_pk_bf16(float lo, float hi) { unsigned r; asm volatile("v_cvt_pk_bf16_f32 %0, %1, %2" : "=v"(r) : "v"(lo), "v"(hi)); return r; }
;     __device__ __forceinline__ void operator()(const f32x4 (&acc)[2][2][4][2], const Unit& u, int wr, int wc, int fr, int fq) const {
;     ...
;             for (int m = 0; m < 4; ++m) { bf16_t* rowp = O + (size_t)(row0 + ai * HALF + m * 16) * ldc + col0;
;                 const float rs = rowss ? sc * (1.0f / sqrtf((float)__hip_atomic_load(rowss + row0 + ai * HALF + m * 16, __ATOMIC_RELAXED, __HIP_MEMORY_SCOPE_AGENT) * (1.0f / (2048.0f * 1048576.0f)) + 1e-6f)) : sc;
; #pragma unroll
;                 for (int bj = 0; bj < 2; ++bj) { f32x4 v0 = acc[ai][bj][m][0] * rs, v1 = acc[ai][bj][m][1] * rs;
;                     if (ACT == 1) {
; #pragma unroll
;                         for (int e = 0; e < 4; ++e) { float a = v0[e] > 0.f ? v0[e] : 0.f; v0[e] = a * a; float b = v1[e] > 0.f ? v1[e] : 0.f; v1[e] = b * b; } }
;                     u32x4 w; w.x = cvt_pk_bf16(v0[0], v0[1]); w.y = cvt_pk_bf16(v0[2], v0[3]); w.z = cvt_pk_bf16(v1[0], v1[1]); w.w = cvt_pk_bf16(v1[2], v1[3]);
;                     *(u32x4*)(rowp + bj * HALF) = w; } }
.LBB0_140:
	s_nop 0
	v_or_b32_e32 v114, 16, v138
	v_mov_b64_e32 v[112:113], s[78:79]
	v_mad_i64_i32 v[112:113], s[6:7], v114, s91, v[112:113]
	v_lshl_add_u64 v[112:113], v[142:143], 1, v[112:113]
	v_pk_mul_f32 v[110:111], v[110:111], v[144:145] op_sel_hi:[1,0]
	v_pk_mul_f32 v[108:109], v[108:109], v[144:145] op_sel_hi:[1,0]
	v_pk_mul_f32 v[114:115], v[106:107], v[144:145] op_sel_hi:[1,0]
	v_pk_mul_f32 v[106:107], v[104:105], v[144:145] op_sel_hi:[1,0]
	v_cvt_pk_bf16_f32 v104, v108, v109
	v_cvt_pk_bf16_f32 v105, v110, v111
	v_pk_mul_f32 v[102:103], v[102:103], v[144:145] op_sel_hi:[1,0]
	v_cvt_pk_bf16_f32 v106, v106, v107
	v_cvt_pk_bf16_f32 v107, v114, v115
	global_store_dwordx4 v[112:113], v[104:107], off
	v_pk_mul_f32 v[100:101], v[100:101], v[144:145] op_sel_hi:[1,0]
	s_and_b64 vcc, exec, s[4:5]
	v_pk_mul_f32 v[104:105], v[98:99], v[144:145] op_sel_hi:[1,0]
	v_pk_mul_f32 v[98:99], v[96:97], v[144:145] op_sel_hi:[1,0]
	v_cvt_pk_bf16_f32 v96, v100, v101
	v_cvt_pk_bf16_f32 v97, v102, v103
	s_nop 0
	v_cvt_pk_bf16_f32 v98, v98, v99
	v_cvt_pk_bf16_f32 v99, v104, v105
	global_store_dwordx4 v[112:113], v[96:99], off offset:256
	s_nop 1
	v_mov_b32_e32 v96, 1.0
	v_mov_b32_e32 v98, 1.0
	s_cbranch_vccnz .LBB0_142
	s_waitcnt vmcnt(9)
	s_nop 0
	v_mov_b32_e32 v98, v160
	v_mov_b32_e32 v99, v161
	v_ffbh_u32_e32 v97, v99
	v_min_u32_e32 v97, 32, v97
	v_lshlrev_b64 v[98:99], v97, v[98:99]
	v_min_u32_e32 v98, 1, v98
	v_or_b32_e32 v98, v99, v98
	v_cvt_f32_u32_e32 v98, v98
	v_sub_u32_e32 v97, 32, v97
	v_ldexp_f32 v97, v98, v97
	v_fmamk_f32 v97, v97, 0x30000000, v208
	v_mul_f32_e32 v98, 0x4f800000, v97
	v_cmp_gt_f32_e32 vcc, s33, v97
	s_nop 1
	v_cndmask_b32_e32 v97, v97, v98, vcc
	v_sqrt_f32_e32 v98, v97
	s_nop 0
	v_add_u32_e32 v99, -1, v98
	v_add_u32_e32 v100, 1, v98
	v_fma_f32 v101, -v99, v98, v97
	v_fma_f32 v102, -v100, v98, v97
	v_cmp_ge_f32_e64 s[6:7], 0, v101
	s_nop 1
	v_cndmask_b32_e64 v98, v98, v99, s[6:7]
	v_cmp_lt_f32_e64 s[6:7], 0, v102
	s_nop 1
	v_cndmask_b32_e64 v98, v98, v100, s[6:7]
	v_mul_f32_e32 v99, 0x37800000, v98
	v_cndmask_b32_e32 v98, v98, v99, vcc
	v_cmp_class_f32_e32 vcc, v97, v209
	s_nop 1
	v_cndmask_b32_e32 v97, v98, v97, vcc
	v_div_scale_f32 v98, s[6:7], v97, v97, 1.0
	v_rcp_f32_e32 v99, v98
	v_div_scale_f32 v100, vcc, 1.0, v97, 1.0
	v_fma_f32 v101, -v98, v99, 1.0
	v_fmac_f32_e32 v99, v101, v99
	v_mul_f32_e32 v101, v100, v99
	v_fma_f32 v102, -v98, v101, v100
	v_fmac_f32_e32 v101, v102, v99
	v_fma_f32 v98, -v98, v101, v100
	v_div_fmas_f32 v98, v98, v99, v101
	v_div_fixup_f32 v98, v98, v97, 1.0
.LBB0_142:
	v_or_b32_e32 v97, 32, v138
	v_mov_b64_e32 v[100:101], s[78:79]
	v_mad_i64_i32 v[100:101], s[6:7], v97, s91, v[100:101]
	v_lshl_add_u64 v[100:101], v[142:143], 1, v[100:101]
	v_pk_mul_f32 v[94:95], v[94:95], v[98:99] op_sel_hi:[1,0]
	v_pk_mul_f32 v[92:93], v[92:93], v[98:99] op_sel_hi:[1,0]
	v_pk_mul_f32 v[102:103], v[90:91], v[98:99] op_sel_hi:[1,0]
	v_pk_mul_f32 v[90:91], v[88:89], v[98:99] op_sel_hi:[1,0]
	v_cvt_pk_bf16_f32 v88, v92, v93
	v_cvt_pk_bf16_f32 v89, v94, v95
	s_and_b64 vcc, exec, s[4:5]
	v_cvt_pk_bf16_f32 v90, v90, v91
	v_cvt_pk_bf16_f32 v91, v102, v103
	global_store_dwordx4 v[100:101], v[88:91], off
	v_pk_mul_f32 v[86:87], v[86:87], v[98:99] op_sel_hi:[1,0]
	v_pk_mul_f32 v[84:85], v[84:85], v[98:99] op_sel_hi:[1,0]
	v_pk_mul_f32 v[88:89], v[82:83], v[98:99] op_sel_hi:[1,0]
	v_pk_mul_f32 v[82:83], v[80:81], v[98:99] op_sel_hi:[1,0]
	v_cvt_pk_bf16_f32 v80, v84, v85
	v_cvt_pk_bf16_f32 v81, v86, v87
	s_nop 0
	v_cvt_pk_bf16_f32 v82, v82, v83
	v_cvt_pk_bf16_f32 v83, v88, v89
	global_store_dwordx4 v[100:101], v[80:83], off offset:256
	s_cbranch_vccnz .LBB0_144
	s_waitcnt vmcnt(10)
	s_nop 0
	v_mov_b32_e32 v80, v162
	v_mov_b32_e32 v81, v163
	v_ffbh_u32_e32 v82, v81
	v_min_u32_e32 v82, 32, v82
	v_lshlrev_b64 v[80:81], v82, v[80:81]
	v_min_u32_e32 v80, 1, v80
	v_or_b32_e32 v80, v81, v80
	v_cvt_f32_u32_e32 v80, v80
	v_sub_u32_e32 v81, 32, v82
	v_ldexp_f32 v80, v80, v81
	v_fmamk_f32 v80, v80, 0x30000000, v208
	v_mul_f32_e32 v81, 0x4f800000, v80
	v_cmp_gt_f32_e32 vcc, s33, v80
	s_nop 1
	v_cndmask_b32_e32 v80, v80, v81, vcc
	v_sqrt_f32_e32 v81, v80
	s_nop 0
	v_add_u32_e32 v82, -1, v81
	v_add_u32_e32 v83, 1, v81
	v_fma_f32 v84, -v82, v81, v80
	v_fma_f32 v85, -v83, v81, v80
	v_cmp_ge_f32_e64 s[6:7], 0, v84
	s_nop 1
	v_cndmask_b32_e64 v81, v81, v82, s[6:7]
	v_cmp_lt_f32_e64 s[6:7], 0, v85
	s_nop 1
	v_cndmask_b32_e64 v81, v81, v83, s[6:7]
	v_mul_f32_e32 v82, 0x37800000, v81
	v_cndmask_b32_e32 v81, v81, v82, vcc
	v_cmp_class_f32_e32 vcc, v80, v209
	s_nop 1
	v_cndmask_b32_e32 v80, v81, v80, vcc
	v_div_scale_f32 v81, s[6:7], v80, v80, 1.0
	v_rcp_f32_e32 v82, v81
	v_div_scale_f32 v83, vcc, 1.0, v80, 1.0
	v_fma_f32 v84, -v81, v82, 1.0
	v_fmac_f32_e32 v82, v84, v82
	v_mul_f32_e32 v84, v83, v82
	v_fma_f32 v85, -v81, v84, v83
	v_fmac_f32_e32 v84, v85, v82
	v_fma_f32 v81, -v81, v84, v83
	v_div_fmas_f32 v81, v81, v82, v84
	v_div_fixup_f32 v96, v81, v80, 1.0
; __device__ __forceinline__ unsigned cvt_pk_bf16(float lo, float hi) { unsigned r; asm volatile("v_cvt_pk_bf16_f32 %0, %1, %2" : "=v"(r) : "v"(lo), "v"(hi)); return r; }
;     __device__ __forceinline__ void operator()(const f32x4 (&acc)[2][2][4][2], const Unit& u, int wr, int wc, int fr, int fq) const {
;     ...
;             for (int m = 0; m < 4; ++m) { bf16_t* rowp = O + (size_t)(row0 + ai * HALF + m * 16) * ldc + col0;
;                 const float rs = rowss ? sc * (1.0f / sqrtf((float)__hip_atomic_load(rowss + row0 + ai * HALF + m * 16, __ATOMIC_RELAXED, __HIP_MEMORY_SCOPE_AGENT) * (1.0f / (2048.0f * 1048576.0f)) + 1e-6f)) : sc;
; #pragma unroll
;                 for (int bj = 0; bj < 2; ++bj) { f32x4 v0 = acc[ai][bj][m][0] * rs, v1 = acc[ai][bj][m][1] * rs;
;                     if (ACT == 1) {
; #pragma unroll
;                         for (int e = 0; e < 4; ++e) { float a = v0[e] > 0.f ? v0[e] : 0.f; v0[e] = a * a; float b = v1[e] > 0.f ? v1[e] : 0.f; v1[e] = b * b; } }
;                     u32x4 w; w.x = cvt_pk_bf16(v0[0], v0[1]); w.y = cvt_pk_bf16(v0[2], v0[3]); w.z = cvt_pk_bf16(v1[0], v1[1]); w.w = cvt_pk_bf16(v1[2], v1[3]);
;                     *(u32x4*)(rowp + bj * HALF) = w; } }
.LBB0_144:
	s_nop 0
	v_or_b32_e32 v82, 48, v138
	v_mov_b64_e32 v[80:81], s[78:79]
	v_mad_i64_i32 v[80:81], s[6:7], v82, s91, v[80:81]
	v_lshl_add_u64 v[80:81], v[142:143], 1, v[80:81]
	v_pk_mul_f32 v[78:79], v[78:79], v[96:97] op_sel_hi:[1,0]
	v_pk_mul_f32 v[76:77], v[76:77], v[96:97] op_sel_hi:[1,0]
	v_pk_mul_f32 v[82:83], v[74:75], v[96:97] op_sel_hi:[1,0]
	v_pk_mul_f32 v[74:75], v[72:73], v[96:97] op_sel_hi:[1,0]
	v_cvt_pk_bf16_f32 v72, v76, v77
	v_cvt_pk_bf16_f32 v73, v78, v79
	v_pk_mul_f32 v[70:71], v[70:71], v[96:97] op_sel_hi:[1,0]
	v_cvt_pk_bf16_f32 v74, v74, v75
	v_cvt_pk_bf16_f32 v75, v82, v83
	global_store_dwordx4 v[80:81], v[72:75], off
	v_pk_mul_f32 v[68:69], v[68:69], v[96:97] op_sel_hi:[1,0]
	s_and_b64 vcc, exec, s[4:5]
	v_pk_mul_f32 v[72:73], v[66:67], v[96:97] op_sel_hi:[1,0]
	v_pk_mul_f32 v[66:67], v[64:65], v[96:97] op_sel_hi:[1,0]
	v_cvt_pk_bf16_f32 v64, v68, v69
	v_cvt_pk_bf16_f32 v65, v70, v71
	s_nop 0
	v_cvt_pk_bf16_f32 v66, v66, v67
	v_cvt_pk_bf16_f32 v67, v72, v73
	global_store_dwordx4 v[80:81], v[64:67], off offset:256
	s_nop 1
	v_mov_b32_e32 v64, 1.0
	v_mov_b32_e32 v66, 1.0
	s_cbranch_vccnz .LBB0_146
	s_waitcnt vmcnt(11)
	s_nop 0
	v_mov_b32_e32 v66, v164
	v_mov_b32_e32 v67, v165
	v_ffbh_u32_e32 v65, v67
	v_min_u32_e32 v65, 32, v65
	v_lshlrev_b64 v[66:67], v65, v[66:67]
	v_min_u32_e32 v66, 1, v66
	v_or_b32_e32 v66, v67, v66
	v_cvt_f32_u32_e32 v66, v66
	v_sub_u32_e32 v65, 32, v65
	v_ldexp_f32 v65, v66, v65
	v_fmamk_f32 v65, v65, 0x30000000, v208
	v_mul_f32_e32 v66, 0x4f800000, v65
	v_cmp_gt_f32_e32 vcc, s33, v65
	s_nop 1
	v_cndmask_b32_e32 v65, v65, v66, vcc
	v_sqrt_f32_e32 v66, v65
	s_nop 0
	v_add_u32_e32 v67, -1, v66
	v_add_u32_e32 v68, 1, v66
	v_fma_f32 v69, -v67, v66, v65
	v_fma_f32 v70, -v68, v66, v65
	v_cmp_ge_f32_e64 s[6:7], 0, v69
	s_nop 1
	v_cndmask_b32_e64 v66, v66, v67, s[6:7]
	v_cmp_lt_f32_e64 s[6:7], 0, v70
	s_nop 1
	v_cndmask_b32_e64 v66, v66, v68, s[6:7]
	v_mul_f32_e32 v67, 0x37800000, v66
	v_cndmask_b32_e32 v66, v66, v67, vcc
	v_cmp_class_f32_e32 vcc, v65, v209
	s_nop 1
	v_cndmask_b32_e32 v65, v66, v65, vcc
	v_div_scale_f32 v66, s[6:7], v65, v65, 1.0
	v_rcp_f32_e32 v67, v66
	v_div_scale_f32 v68, vcc, 1.0, v65, 1.0
	v_fma_f32 v69, -v66, v67, 1.0
	v_fmac_f32_e32 v67, v69, v67
	v_mul_f32_e32 v69, v68, v67
	v_fma_f32 v70, -v66, v69, v68
	v_fmac_f32_e32 v69, v70, v67
	v_fma_f32 v66, -v66, v69, v68
	v_div_fmas_f32 v66, v66, v67, v69
	v_div_fixup_f32 v66, v66, v65, 1.0
.LBB0_146:
	v_add_u32_e32 v65, 0x80, v138
	v_mov_b64_e32 v[68:69], s[78:79]
	v_mad_i64_i32 v[68:69], s[6:7], v65, s91, v[68:69]
	v_lshl_add_u64 v[68:69], v[142:143], 1, v[68:69]
	v_pk_mul_f32 v[62:63], v[62:63], v[66:67] op_sel_hi:[1,0]
	v_pk_mul_f32 v[60:61], v[60:61], v[66:67] op_sel_hi:[1,0]
	v_pk_mul_f32 v[70:71], v[58:59], v[66:67] op_sel_hi:[1,0]
	v_pk_mul_f32 v[58:59], v[56:57], v[66:67] op_sel_hi:[1,0]
	v_cvt_pk_bf16_f32 v56, v60, v61
	v_cvt_pk_bf16_f32 v57, v62, v63
	s_and_b64 vcc, exec, s[4:5]
	v_cvt_pk_bf16_f32 v58, v58, v59
	v_cvt_pk_bf16_f32 v59, v70, v71
	global_store_dwordx4 v[68:69], v[56:59], off
	v_pk_mul_f32 v[54:55], v[54:55], v[66:67] op_sel_hi:[1,0]
	v_pk_mul_f32 v[52:53], v[52:53], v[66:67] op_sel_hi:[1,0]
	v_pk_mul_f32 v[56:57], v[50:51], v[66:67] op_sel_hi:[1,0]
	v_pk_mul_f32 v[50:51], v[48:49], v[66:67] op_sel_hi:[1,0]
	v_cvt_pk_bf16_f32 v48, v52, v53
	v_cvt_pk_bf16_f32 v49, v54, v55
	s_nop 0
	v_cvt_pk_bf16_f32 v50, v50, v51
	v_cvt_pk_bf16_f32 v51, v56, v57
	global_store_dwordx4 v[68:69], v[48:51], off offset:256
	s_cbranch_vccnz .LBB0_148
	s_waitcnt vmcnt(12)
	s_nop 0
	v_mov_b32_e32 v48, v166
	v_mov_b32_e32 v49, v167
	v_ffbh_u32_e32 v50, v49
	v_min_u32_e32 v50, 32, v50
	v_lshlrev_b64 v[48:49], v50, v[48:49]
	v_min_u32_e32 v48, 1, v48
	v_or_b32_e32 v48, v49, v48
	v_cvt_f32_u32_e32 v48, v48
	v_sub_u32_e32 v49, 32, v50
	v_ldexp_f32 v48, v48, v49
	v_fmamk_f32 v48, v48, 0x30000000, v208
	v_mul_f32_e32 v49, 0x4f800000, v48
	v_cmp_gt_f32_e32 vcc, s33, v48
	s_nop 1
	v_cndmask_b32_e32 v48, v48, v49, vcc
	v_sqrt_f32_e32 v49, v48
	s_nop 0
	v_add_u32_e32 v50, -1, v49
	v_add_u32_e32 v51, 1, v49
	v_fma_f32 v52, -v50, v49, v48
	v_fma_f32 v53, -v51, v49, v48
	v_cmp_ge_f32_e64 s[6:7], 0, v52
	s_nop 1
	v_cndmask_b32_e64 v49, v49, v50, s[6:7]
	v_cmp_lt_f32_e64 s[6:7], 0, v53
	s_nop 1
	v_cndmask_b32_e64 v49, v49, v51, s[6:7]
	v_mul_f32_e32 v50, 0x37800000, v49
	v_cndmask_b32_e32 v49, v49, v50, vcc
	v_cmp_class_f32_e32 vcc, v48, v209
	s_nop 1
	v_cndmask_b32_e32 v48, v49, v48, vcc
	v_div_scale_f32 v49, s[6:7], v48, v48, 1.0
	v_rcp_f32_e32 v50, v49
	v_div_scale_f32 v51, vcc, 1.0, v48, 1.0
	v_fma_f32 v52, -v49, v50, 1.0
	v_fmac_f32_e32 v50, v52, v50
	v_mul_f32_e32 v52, v51, v50
	v_fma_f32 v53, -v49, v52, v51
	v_fmac_f32_e32 v52, v53, v50
	v_fma_f32 v49, -v49, v52, v51
	v_div_fmas_f32 v49, v49, v50, v52
	v_div_fixup_f32 v64, v49, v48, 1.0
; __device__ __forceinline__ unsigned cvt_pk_bf16(float lo, float hi) { unsigned r; asm volatile("v_cvt_pk_bf16_f32 %0, %1, %2" : "=v"(r) : "v"(lo), "v"(hi)); return r; }
;     __device__ __forceinline__ void operator()(const f32x4 (&acc)[2][2][4][2], const Unit& u, int wr, int wc, int fr, int fq) const {
;     ...
;             for (int m = 0; m < 4; ++m) { bf16_t* rowp = O + (size_t)(row0 + ai * HALF + m * 16) * ldc + col0;
;                 const float rs = rowss ? sc * (1.0f / sqrtf((float)__hip_atomic_load(rowss + row0 + ai * HALF + m * 16, __ATOMIC_RELAXED, __HIP_MEMORY_SCOPE_AGENT) * (1.0f / (2048.0f * 1048576.0f)) + 1e-6f)) : sc;
; #pragma unroll
;                 for (int bj = 0; bj < 2; ++bj) { f32x4 v0 = acc[ai][bj][m][0] * rs, v1 = acc[ai][bj][m][1] * rs;
;                     if (ACT == 1) {
; #pragma unroll
;                         for (int e = 0; e < 4; ++e) { float a = v0[e] > 0.f ? v0[e] : 0.f; v0[e] = a * a; float b = v1[e] > 0.f ? v1[e] : 0.f; v1[e] = b * b; } }
;                     u32x4 w; w.x = cvt_pk_bf16(v0[0], v0[1]); w.y = cvt_pk_bf16(v0[2], v0[3]); w.z = cvt_pk_bf16(v1[0], v1[1]); w.w = cvt_pk_bf16(v1[2], v1[3]);
;                     *(u32x4*)(rowp + bj * HALF) = w; } }
.LBB0_148:
	s_nop 0
	v_add_u32_e32 v50, 0x90, v138
	v_mov_b64_e32 v[48:49], s[78:79]
	v_mad_i64_i32 v[48:49], s[6:7], v50, s91, v[48:49]
	v_lshl_add_u64 v[48:49], v[142:143], 1, v[48:49]
	v_pk_mul_f32 v[46:47], v[46:47], v[64:65] op_sel_hi:[1,0]
	v_pk_mul_f32 v[44:45], v[44:45], v[64:65] op_sel_hi:[1,0]
	v_pk_mul_f32 v[50:51], v[42:43], v[64:65] op_sel_hi:[1,0]
	v_pk_mul_f32 v[42:43], v[40:41], v[64:65] op_sel_hi:[1,0]
	v_cvt_pk_bf16_f32 v40, v44, v45
	v_cvt_pk_bf16_f32 v41, v46, v47
	v_pk_mul_f32 v[38:39], v[38:39], v[64:65] op_sel_hi:[1,0]
	v_cvt_pk_bf16_f32 v42, v42, v43
	v_cvt_pk_bf16_f32 v43, v50, v51
	global_store_dwordx4 v[48:49], v[40:43], off
	v_pk_mul_f32 v[36:37], v[36:37], v[64:65] op_sel_hi:[1,0]
	s_and_b64 vcc, exec, s[4:5]
	v_pk_mul_f32 v[40:41], v[34:35], v[64:65] op_sel_hi:[1,0]
	v_pk_mul_f32 v[34:35], v[32:33], v[64:65] op_sel_hi:[1,0]
	v_cvt_pk_bf16_f32 v32, v36, v37
	v_cvt_pk_bf16_f32 v33, v38, v39
	s_nop 0
	v_cvt_pk_bf16_f32 v34, v34, v35
	v_cvt_pk_bf16_f32 v35, v40, v41
	global_store_dwordx4 v[48:49], v[32:35], off offset:256
	s_nop 1
	v_mov_b32_e32 v32, 1.0
	v_mov_b32_e32 v34, 1.0
	s_cbranch_vccnz .LBB0_150
	s_waitcnt vmcnt(13)
	s_nop 0
	v_mov_b32_e32 v34, v168
	v_mov_b32_e32 v35, v169
	v_ffbh_u32_e32 v33, v35
	v_min_u32_e32 v33, 32, v33
	v_lshlrev_b64 v[34:35], v33, v[34:35]
	v_min_u32_e32 v34, 1, v34
	v_or_b32_e32 v34, v35, v34
	v_cvt_f32_u32_e32 v34, v34
	v_sub_u32_e32 v33, 32, v33
	v_ldexp_f32 v33, v34, v33
	v_fmamk_f32 v33, v33, 0x30000000, v208
	v_mul_f32_e32 v34, 0x4f800000, v33
	v_cmp_gt_f32_e32 vcc, s33, v33
	s_nop 1
	v_cndmask_b32_e32 v33, v33, v34, vcc
	v_sqrt_f32_e32 v34, v33
	s_nop 0
	v_add_u32_e32 v35, -1, v34
	v_add_u32_e32 v36, 1, v34
	v_fma_f32 v37, -v35, v34, v33
	v_fma_f32 v38, -v36, v34, v33
	v_cmp_ge_f32_e64 s[6:7], 0, v37
	s_nop 1
	v_cndmask_b32_e64 v34, v34, v35, s[6:7]
	v_cmp_lt_f32_e64 s[6:7], 0, v38
	s_nop 1
	v_cndmask_b32_e64 v34, v34, v36, s[6:7]
	v_mul_f32_e32 v35, 0x37800000, v34
	v_cndmask_b32_e32 v34, v34, v35, vcc
	v_cmp_class_f32_e32 vcc, v33, v209
	s_nop 1
	v_cndmask_b32_e32 v33, v34, v33, vcc
	v_div_scale_f32 v34, s[6:7], v33, v33, 1.0
	v_rcp_f32_e32 v35, v34
	v_div_scale_f32 v36, vcc, 1.0, v33, 1.0
	v_fma_f32 v37, -v34, v35, 1.0
	v_fmac_f32_e32 v35, v37, v35
	v_mul_f32_e32 v37, v36, v35
	v_fma_f32 v38, -v34, v37, v36
	v_fmac_f32_e32 v37, v38, v35
	v_fma_f32 v34, -v34, v37, v36
	v_div_fmas_f32 v34, v34, v35, v37
	v_div_fixup_f32 v34, v34, v33, 1.0
.LBB0_150:
	v_add_u32_e32 v33, 0xa0, v138
	v_mov_b64_e32 v[36:37], s[78:79]
	v_mad_i64_i32 v[36:37], s[6:7], v33, s91, v[36:37]
	v_lshl_add_u64 v[36:37], v[142:143], 1, v[36:37]
	v_pk_mul_f32 v[30:31], v[30:31], v[34:35] op_sel_hi:[1,0]
	v_pk_mul_f32 v[28:29], v[28:29], v[34:35] op_sel_hi:[1,0]
	v_pk_mul_f32 v[38:39], v[26:27], v[34:35] op_sel_hi:[1,0]
	v_pk_mul_f32 v[26:27], v[24:25], v[34:35] op_sel_hi:[1,0]
	v_cvt_pk_bf16_f32 v24, v28, v29
	v_cvt_pk_bf16_f32 v25, v30, v31
	s_and_b64 vcc, exec, s[4:5]
	v_cvt_pk_bf16_f32 v26, v26, v27
	v_cvt_pk_bf16_f32 v27, v38, v39
	global_store_dwordx4 v[36:37], v[24:27], off
	v_pk_mul_f32 v[22:23], v[22:23], v[34:35] op_sel_hi:[1,0]
	v_pk_mul_f32 v[20:21], v[20:21], v[34:35] op_sel_hi:[1,0]
	v_pk_mul_f32 v[24:25], v[18:19], v[34:35] op_sel_hi:[1,0]
	v_pk_mul_f32 v[18:19], v[16:17], v[34:35] op_sel_hi:[1,0]
	v_cvt_pk_bf16_f32 v16, v20, v21
	v_cvt_pk_bf16_f32 v17, v22, v23
	s_nop 0
	v_cvt_pk_bf16_f32 v18, v18, v19
	v_cvt_pk_bf16_f32 v19, v24, v25
	global_store_dwordx4 v[36:37], v[16:19], off offset:256
	s_cbranch_vccnz .LBB0_152
	s_waitcnt vmcnt(14)
	s_nop 0
	v_mov_b32_e32 v16, v170
	v_mov_b32_e32 v17, v171
	v_ffbh_u32_e32 v18, v17
	v_min_u32_e32 v18, 32, v18
	v_lshlrev_b64 v[16:17], v18, v[16:17]
	v_min_u32_e32 v16, 1, v16
	v_or_b32_e32 v16, v17, v16
	v_cvt_f32_u32_e32 v16, v16
	v_sub_u32_e32 v17, 32, v18
	v_ldexp_f32 v16, v16, v17
	v_fmamk_f32 v16, v16, 0x30000000, v208
	v_mul_f32_e32 v17, 0x4f800000, v16
	v_cmp_gt_f32_e32 vcc, s33, v16
	s_nop 1
	v_cndmask_b32_e32 v16, v16, v17, vcc
	v_sqrt_f32_e32 v17, v16
	s_nop 0
	v_add_u32_e32 v18, -1, v17
	v_add_u32_e32 v19, 1, v17
	v_fma_f32 v20, -v18, v17, v16
	v_fma_f32 v21, -v19, v17, v16
	v_cmp_ge_f32_e64 s[4:5], 0, v20
	s_nop 1
	v_cndmask_b32_e64 v17, v17, v18, s[4:5]
	v_cmp_lt_f32_e64 s[4:5], 0, v21
	s_nop 1
	v_cndmask_b32_e64 v17, v17, v19, s[4:5]
	v_mul_f32_e32 v18, 0x37800000, v17
	v_cndmask_b32_e32 v17, v17, v18, vcc
	v_cmp_class_f32_e32 vcc, v16, v209
	s_nop 1
	v_cndmask_b32_e32 v16, v17, v16, vcc
	v_div_scale_f32 v17, s[4:5], v16, v16, 1.0
	v_rcp_f32_e32 v18, v17
	v_div_scale_f32 v19, vcc, 1.0, v16, 1.0
	v_fma_f32 v20, -v17, v18, 1.0
	v_fmac_f32_e32 v18, v20, v18
	v_mul_f32_e32 v20, v19, v18
	v_fma_f32 v21, -v17, v20, v19
	v_fmac_f32_e32 v20, v21, v18
	v_fma_f32 v17, -v17, v20, v19
	v_div_fmas_f32 v17, v17, v18, v20
	v_div_fixup_f32 v32, v17, v16, 1.0

; __device__ __forceinline__ unsigned cvt_pk_bf16(float lo, float hi) { unsigned r; asm volatile("v_cvt_pk_bf16_f32 %0, %1, %2" : "=v"(r) : "v"(lo), "v"(hi)); return r; }
;     __device__ __forceinline__ void operator()(const f32x4 (&acc)[2][2][4][2], const Unit& u, int wr, int wc, int fr, int fq) const {
;         const int row0 = u.pm * BM + wr * 64 + fr; const int colt = u.pn * BM;
;         const float sc = (colt < scale_cols) ? scale0 : 1.f;
;         const int col0 = colt + wc * 32 + 8 * fq;
; #pragma unroll
;         for (int ai = 0; ai < 2; ++ai)
; #pragma unroll
;             for (int m = 0; m < 4; ++m) { bf16_t* rowp = O + (size_t)(row0 + ai * HALF + m * 16) * ldc + col0;
;                 const float rs = rowss ? sc * (1.0f / sqrtf((float)__hip_atomic_load(rowss + row0 + ai * HALF + m * 16, __ATOMIC_RELAXED, __HIP_MEMORY_SCOPE_AGENT) * (1.0f / (2048.0f * 1048576.0f)) + 1e-6f)) : sc;
; #pragma unroll
;                 for (int bj = 0; bj < 2; ++bj) { f32x4 v0 = acc[ai][bj][m][0] * rs, v1 = acc[ai][bj][m][1] * rs;
;                     if (ACT == 1) {
; #pragma unroll
;                         for (int e = 0; e < 4; ++e) { float a = v0[e] > 0.f ? v0[e] : 0.f; v0[e] = a * a; float b = v1[e] > 0.f ? v1[e] : 0.f; v1[e] = b * b; } }
;                     u32x4 w; w.x = cvt_pk_bf16(v0[0], v0[1]); w.y = cvt_pk_bf16(v0[2], v0[3]); w.z = cvt_pk_bf16(v1[0], v1[1]); w.w = cvt_pk_bf16(v1[2], v1[3]);
;                     *(u32x4*)(rowp + bj * HALF) = w; } }
.LBB0_170:
	s_cmp_lt_i32 s38, 8
	v_lshl_add_u32 v140, s39, 8, v139
	s_cselect_b64 vcc, -1, 0
	v_cndmask_b32_e32 v138, 1.0, v211, vcc
	v_ashrrev_i32_e32 v141, 31, v140
	v_cndmask_b32_e64 v142, 0, 1, s[8:9]
	v_cmp_ne_u32_e64 s[4:5], 1, v142
	s_andn2_b64 vcc, exec, s[8:9]
	v_lshl_add_u64 v[144:145], v[140:141], 3, s[10:11]
	v_mov_b32_e32 v146, v138
	s_cbranch_vccnz .LBB0_172
	global_load_dwordx2 v[156:157], v[144:145], off sc1
	global_load_dwordx2 v[158:159], v[144:145], off offset:128 sc1
	global_load_dwordx2 v[160:161], v[144:145], off offset:256 sc1
	global_load_dwordx2 v[162:163], v[144:145], off offset:384 sc1
	global_load_dwordx2 v[164:165], v[144:145], off offset:1024 sc1
	global_load_dwordx2 v[166:167], v[144:145], off offset:1152 sc1
	global_load_dwordx2 v[168:169], v[144:145], off offset:1280 sc1
	global_load_dwordx2 v[170:171], v[144:145], off offset:1408 sc1
	s_waitcnt vmcnt(7)
	v_mov_b32_e32 v142, v156
	v_mov_b32_e32 v143, v157
	v_ffbh_u32_e32 v141, v143
	v_min_u32_e32 v141, 32, v141
	v_lshlrev_b64 v[142:143], v141, v[142:143]
	v_min_u32_e32 v142, 1, v142
	v_or_b32_e32 v142, v143, v142
	v_cvt_f32_u32_e32 v142, v142
	v_sub_u32_e32 v141, 32, v141
	v_ldexp_f32 v141, v142, v141
	v_fmamk_f32 v141, v141, 0x30000000, v208
	v_mul_f32_e32 v142, 0x4f800000, v141
	v_cmp_gt_f32_e32 vcc, s33, v141
	s_nop 1
	v_cndmask_b32_e32 v141, v141, v142, vcc
	v_sqrt_f32_e32 v142, v141
	s_nop 0
	v_add_u32_e32 v143, -1, v142
	v_add_u32_e32 v146, 1, v142
	v_fma_f32 v150, -v143, v142, v141
	v_fma_f32 v151, -v146, v142, v141
	v_cmp_ge_f32_e64 s[6:7], 0, v150
	s_nop 1
	v_cndmask_b32_e64 v142, v142, v143, s[6:7]
	v_cmp_lt_f32_e64 s[6:7], 0, v151
	s_nop 1
	v_cndmask_b32_e64 v142, v142, v146, s[6:7]
	v_mul_f32_e32 v143, 0x37800000, v142
	v_cndmask_b32_e32 v142, v142, v143, vcc
	v_cmp_class_f32_e32 vcc, v141, v209
	s_nop 1
	v_cndmask_b32_e32 v141, v142, v141, vcc
	v_div_scale_f32 v142, s[6:7], v141, v141, 1.0
	v_rcp_f32_e32 v143, v142
	v_div_scale_f32 v146, vcc, 1.0, v141, 1.0
	v_fma_f32 v150, -v142, v143, 1.0
	v_fmac_f32_e32 v143, v150, v143
	v_mul_f32_e32 v150, v146, v143
	v_fma_f32 v151, -v142, v150, v146
	v_fmac_f32_e32 v150, v151, v143
	v_fma_f32 v142, -v142, v150, v146
	v_div_fmas_f32 v142, v142, v143, v150
	v_div_fixup_f32 v141, v142, v141, 1.0
	v_mul_f32_e32 v146, v138, v141
.LBB0_172:
	v_lshl_or_b32 v142, s38, 8, v148
	v_mov_b64_e32 v[150:151], s[78:79]
	v_ashrrev_i32_e32 v143, 31, v142
	v_mad_i64_i32 v[150:151], s[6:7], v140, s92, v[150:151]
	v_lshl_add_u64 v[150:151], v[142:143], 1, v[150:151]
	v_pk_mul_f32 v[126:127], v[126:127], v[146:147] op_sel_hi:[1,0]
	v_pk_mul_f32 v[124:125], v[124:125], v[146:147] op_sel_hi:[1,0]
	v_pk_mul_f32 v[152:153], v[122:123], v[146:147] op_sel_hi:[1,0]
	v_pk_mul_f32 v[122:123], v[120:121], v[146:147] op_sel_hi:[1,0]
	v_cvt_pk_bf16_f32 v120, v124, v125
	v_cvt_pk_bf16_f32 v121, v126, v127
	v_pk_mul_f32 v[116:117], v[116:117], v[146:147] op_sel_hi:[1,0]
	v_cvt_pk_bf16_f32 v122, v122, v123
	v_cvt_pk_bf16_f32 v123, v152, v153
	global_store_dwordx4 v[150:151], v[120:123], off
	v_pk_mul_f32 v[118:119], v[118:119], v[146:147] op_sel_hi:[1,0]
	s_and_b64 vcc, exec, s[4:5]
	v_pk_mul_f32 v[120:121], v[114:115], v[146:147] op_sel_hi:[1,0]
	v_pk_mul_f32 v[114:115], v[112:113], v[146:147] op_sel_hi:[1,0]
	v_cvt_pk_bf16_f32 v112, v116, v117
	v_cvt_pk_bf16_f32 v113, v118, v119
	s_nop 0
	v_cvt_pk_bf16_f32 v114, v114, v115
	v_cvt_pk_bf16_f32 v115, v120, v121
	global_store_dwordx4 v[150:151], v[112:115], off offset:256
	s_nop 1
	v_mov_b32_e32 v112, v138
	s_cbranch_vccnz .LBB0_174
	s_waitcnt vmcnt(8)
	s_nop 0
	v_mov_b32_e32 v112, v158
	v_mov_b32_e32 v113, v159
	v_ffbh_u32_e32 v114, v113
	v_min_u32_e32 v114, 32, v114
	v_lshlrev_b64 v[112:113], v114, v[112:113]
	v_min_u32_e32 v112, 1, v112
	v_or_b32_e32 v112, v113, v112
	v_cvt_f32_u32_e32 v112, v112
	v_sub_u32_e32 v113, 32, v114
	v_ldexp_f32 v112, v112, v113
	v_fmamk_f32 v112, v112, 0x30000000, v208
	v_mul_f32_e32 v113, 0x4f800000, v112
	v_cmp_gt_f32_e32 vcc, s33, v112
	s_nop 1
	v_cndmask_b32_e32 v112, v112, v113, vcc
	v_sqrt_f32_e32 v113, v112
	s_nop 0
	v_add_u32_e32 v114, -1, v113
	v_add_u32_e32 v115, 1, v113
	v_fma_f32 v116, -v114, v113, v112
	v_fma_f32 v117, -v115, v113, v112
	v_cmp_ge_f32_e64 s[6:7], 0, v116
	s_nop 1
	v_cndmask_b32_e64 v113, v113, v114, s[6:7]
	v_cmp_lt_f32_e64 s[6:7], 0, v117
	s_nop 1
	v_cndmask_b32_e64 v113, v113, v115, s[6:7]
	v_mul_f32_e32 v114, 0x37800000, v113
	v_cndmask_b32_e32 v113, v113, v114, vcc
	v_cmp_class_f32_e32 vcc, v112, v209
	s_nop 1
	v_cndmask_b32_e32 v112, v113, v112, vcc
	v_div_scale_f32 v113, s[6:7], v112, v112, 1.0
	v_rcp_f32_e32 v114, v113
	v_div_scale_f32 v115, vcc, 1.0, v112, 1.0
	v_fma_f32 v116, -v113, v114, 1.0
	v_fmac_f32_e32 v114, v116, v114
	v_mul_f32_e32 v116, v115, v114
	v_fma_f32 v117, -v113, v116, v115
	v_fmac_f32_e32 v116, v117, v114
	v_fma_f32 v113, -v113, v116, v115
	v_div_fmas_f32 v113, v113, v114, v116
	v_div_fixup_f32 v112, v113, v112, 1.0
	v_mul_f32_e32 v112, v138, v112
; __device__ __forceinline__ unsigned cvt_pk_bf16(float lo, float hi) { unsigned r; asm volatile("v_cvt_pk_bf16_f32 %0, %1, %2" : "=v"(r) : "v"(lo), "v"(hi)); return r; }
;     __device__ __forceinline__ void operator()(const f32x4 (&acc)[2][2][4][2], const Unit& u, int wr, int wc, int fr, int fq) const {
;     ...
;             for (int m = 0; m < 4; ++m) { bf16_t* rowp = O + (size_t)(row0 + ai * HALF + m * 16) * ldc + col0;
;                 const float rs = rowss ? sc * (1.0f / sqrtf((float)__hip_atomic_load(rowss + row0 + ai * HALF + m * 16, __ATOMIC_RELAXED, __HIP_MEMORY_SCOPE_AGENT) * (1.0f / (2048.0f * 1048576.0f)) + 1e-6f)) : sc;
; #pragma unroll
;                 for (int bj = 0; bj < 2; ++bj) { f32x4 v0 = acc[ai][bj][m][0] * rs, v1 = acc[ai][bj][m][1] * rs;
;                     if (ACT == 1) {
; #pragma unroll
;                         for (int e = 0; e < 4; ++e) { float a = v0[e] > 0.f ? v0[e] : 0.f; v0[e] = a * a; float b = v1[e] > 0.f ? v1[e] : 0.f; v1[e] = b * b; } }
;                     u32x4 w; w.x = cvt_pk_bf16(v0[0], v0[1]); w.y = cvt_pk_bf16(v0[2], v0[3]); w.z = cvt_pk_bf16(v1[0], v1[1]); w.w = cvt_pk_bf16(v1[2], v1[3]);
;                     *(u32x4*)(rowp + bj * HALF) = w; } }
.LBB0_174:
	v_or_b32_e32 v113, 16, v140
	v_mov_b64_e32 v[114:115], s[78:79]
	v_mad_i64_i32 v[114:115], s[6:7], v113, s92, v[114:115]
	v_lshl_add_u64 v[114:115], v[142:143], 1, v[114:115]
	v_pk_mul_f32 v[110:111], v[110:111], v[112:113] op_sel_hi:[1,0]
	v_pk_mul_f32 v[108:109], v[108:109], v[112:113] op_sel_hi:[1,0]
	v_pk_mul_f32 v[116:117], v[106:107], v[112:113] op_sel_hi:[1,0]
	v_pk_mul_f32 v[106:107], v[104:105], v[112:113] op_sel_hi:[1,0]
	v_cvt_pk_bf16_f32 v104, v108, v109
	v_cvt_pk_bf16_f32 v105, v110, v111
	v_pk_mul_f32 v[100:101], v[100:101], v[112:113] op_sel_hi:[1,0]
	v_cvt_pk_bf16_f32 v106, v106, v107
	v_cvt_pk_bf16_f32 v107, v116, v117
	global_store_dwordx4 v[114:115], v[104:107], off
	v_pk_mul_f32 v[102:103], v[102:103], v[112:113] op_sel_hi:[1,0]
	s_and_b64 vcc, exec, s[4:5]
	v_pk_mul_f32 v[104:105], v[98:99], v[112:113] op_sel_hi:[1,0]
	v_pk_mul_f32 v[98:99], v[96:97], v[112:113] op_sel_hi:[1,0]
	v_cvt_pk_bf16_f32 v96, v100, v101
	v_cvt_pk_bf16_f32 v97, v102, v103
	s_nop 0
	v_cvt_pk_bf16_f32 v98, v98, v99
	v_cvt_pk_bf16_f32 v99, v104, v105
	global_store_dwordx4 v[114:115], v[96:99], off offset:256
	s_nop 1
	v_mov_b32_e32 v96, v138
	s_cbranch_vccnz .LBB0_176
	s_waitcnt vmcnt(9)
	s_nop 0
	v_mov_b32_e32 v96, v160
	v_mov_b32_e32 v97, v161
	v_ffbh_u32_e32 v98, v97
	v_min_u32_e32 v98, 32, v98
	v_lshlrev_b64 v[96:97], v98, v[96:97]
	v_min_u32_e32 v96, 1, v96
	v_or_b32_e32 v96, v97, v96
	v_cvt_f32_u32_e32 v96, v96
	v_sub_u32_e32 v97, 32, v98
	v_ldexp_f32 v96, v96, v97
	v_fmamk_f32 v96, v96, 0x30000000, v208
	v_mul_f32_e32 v97, 0x4f800000, v96
	v_cmp_gt_f32_e32 vcc, s33, v96
	s_nop 1
	v_cndmask_b32_e32 v96, v96, v97, vcc
	v_sqrt_f32_e32 v97, v96
	s_nop 0
	v_add_u32_e32 v98, -1, v97
	v_add_u32_e32 v99, 1, v97
	v_fma_f32 v100, -v98, v97, v96
	v_fma_f32 v101, -v99, v97, v96
	v_cmp_ge_f32_e64 s[6:7], 0, v100
	s_nop 1
	v_cndmask_b32_e64 v97, v97, v98, s[6:7]
	v_cmp_lt_f32_e64 s[6:7], 0, v101
	s_nop 1
	v_cndmask_b32_e64 v97, v97, v99, s[6:7]
	v_mul_f32_e32 v98, 0x37800000, v97
	v_cndmask_b32_e32 v97, v97, v98, vcc
	v_cmp_class_f32_e32 vcc, v96, v209
	s_nop 1
	v_cndmask_b32_e32 v96, v97, v96, vcc
	v_div_scale_f32 v97, s[6:7], v96, v96, 1.0
	v_rcp_f32_e32 v98, v97
	v_div_scale_f32 v99, vcc, 1.0, v96, 1.0
	v_fma_f32 v100, -v97, v98, 1.0
	v_fmac_f32_e32 v98, v100, v98
	v_mul_f32_e32 v100, v99, v98
	v_fma_f32 v101, -v97, v100, v99
	v_fmac_f32_e32 v100, v101, v98
	v_fma_f32 v97, -v97, v100, v99
	v_div_fmas_f32 v97, v97, v98, v100
	v_div_fixup_f32 v96, v97, v96, 1.0
	v_mul_f32_e32 v96, v138, v96
.LBB0_176:
	v_or_b32_e32 v97, 32, v140
	v_mov_b64_e32 v[98:99], s[78:79]
	v_mad_i64_i32 v[98:99], s[6:7], v97, s92, v[98:99]
	v_lshl_add_u64 v[98:99], v[142:143], 1, v[98:99]
	v_pk_mul_f32 v[94:95], v[94:95], v[96:97] op_sel_hi:[1,0]
	v_pk_mul_f32 v[92:93], v[92:93], v[96:97] op_sel_hi:[1,0]
	v_pk_mul_f32 v[100:101], v[90:91], v[96:97] op_sel_hi:[1,0]
	v_pk_mul_f32 v[90:91], v[88:89], v[96:97] op_sel_hi:[1,0]
	v_cvt_pk_bf16_f32 v88, v92, v93
	v_cvt_pk_bf16_f32 v89, v94, v95
	v_pk_mul_f32 v[84:85], v[84:85], v[96:97] op_sel_hi:[1,0]
	v_cvt_pk_bf16_f32 v90, v90, v91
	v_cvt_pk_bf16_f32 v91, v100, v101
	global_store_dwordx4 v[98:99], v[88:91], off
	v_pk_mul_f32 v[86:87], v[86:87], v[96:97] op_sel_hi:[1,0]
	s_and_b64 vcc, exec, s[4:5]
	v_pk_mul_f32 v[88:89], v[82:83], v[96:97] op_sel_hi:[1,0]
	v_pk_mul_f32 v[82:83], v[80:81], v[96:97] op_sel_hi:[1,0]
	v_cvt_pk_bf16_f32 v80, v84, v85
	v_cvt_pk_bf16_f32 v81, v86, v87
	s_nop 0
	v_cvt_pk_bf16_f32 v82, v82, v83
	v_cvt_pk_bf16_f32 v83, v88, v89
	global_store_dwordx4 v[98:99], v[80:83], off offset:256
	s_nop 1
	v_mov_b32_e32 v80, v138
	s_cbranch_vccnz .LBB0_178
	s_waitcnt vmcnt(10)
	s_nop 0
	v_mov_b32_e32 v80, v162
	v_mov_b32_e32 v81, v163
	v_ffbh_u32_e32 v82, v81
	v_min_u32_e32 v82, 32, v82
	v_lshlrev_b64 v[80:81], v82, v[80:81]
	v_min_u32_e32 v80, 1, v80
	v_or_b32_e32 v80, v81, v80
	v_cvt_f32_u32_e32 v80, v80
	v_sub_u32_e32 v81, 32, v82
	v_ldexp_f32 v80, v80, v81
	v_fmamk_f32 v80, v80, 0x30000000, v208
	v_mul_f32_e32 v81, 0x4f800000, v80
	v_cmp_gt_f32_e32 vcc, s33, v80
	s_nop 1
	v_cndmask_b32_e32 v80, v80, v81, vcc
	v_sqrt_f32_e32 v81, v80
	s_nop 0
	v_add_u32_e32 v82, -1, v81
	v_add_u32_e32 v83, 1, v81
	v_fma_f32 v84, -v82, v81, v80
	v_fma_f32 v85, -v83, v81, v80
	v_cmp_ge_f32_e64 s[6:7], 0, v84
	s_nop 1
	v_cndmask_b32_e64 v81, v81, v82, s[6:7]
	v_cmp_lt_f32_e64 s[6:7], 0, v85
	s_nop 1
	v_cndmask_b32_e64 v81, v81, v83, s[6:7]
	v_mul_f32_e32 v82, 0x37800000, v81
	v_cndmask_b32_e32 v81, v81, v82, vcc
	v_cmp_class_f32_e32 vcc, v80, v209
	s_nop 1
	v_cndmask_b32_e32 v80, v81, v80, vcc
	v_div_scale_f32 v81, s[6:7], v80, v80, 1.0
	v_rcp_f32_e32 v82, v81
	v_div_scale_f32 v83, vcc, 1.0, v80, 1.0
	v_fma_f32 v84, -v81, v82, 1.0
	v_fmac_f32_e32 v82, v84, v82
	v_mul_f32_e32 v84, v83, v82
	v_fma_f32 v85, -v81, v84, v83
	v_fmac_f32_e32 v84, v85, v82
	v_fma_f32 v81, -v81, v84, v83
	v_div_fmas_f32 v81, v81, v82, v84
	v_div_fixup_f32 v80, v81, v80, 1.0
	v_mul_f32_e32 v80, v138, v80
; __device__ __forceinline__ unsigned cvt_pk_bf16(float lo, float hi) { unsigned r; asm volatile("v_cvt_pk_bf16_f32 %0, %1, %2" : "=v"(r) : "v"(lo), "v"(hi)); return r; }
;     __device__ __forceinline__ void operator()(const f32x4 (&acc)[2][2][4][2], const Unit& u, int wr, int wc, int fr, int fq) const {
;     ...
;             for (int m = 0; m < 4; ++m) { bf16_t* rowp = O + (size_t)(row0 + ai * HALF + m * 16) * ldc + col0;
;                 const float rs = rowss ? sc * (1.0f / sqrtf((float)__hip_atomic_load(rowss + row0 + ai * HALF + m * 16, __ATOMIC_RELAXED, __HIP_MEMORY_SCOPE_AGENT) * (1.0f / (2048.0f * 1048576.0f)) + 1e-6f)) : sc;
; #pragma unroll
;                 for (int bj = 0; bj < 2; ++bj) { f32x4 v0 = acc[ai][bj][m][0] * rs, v1 = acc[ai][bj][m][1] * rs;
;                     if (ACT == 1) {
; #pragma unroll
;                         for (int e = 0; e < 4; ++e) { float a = v0[e] > 0.f ? v0[e] : 0.f; v0[e] = a * a; float b = v1[e] > 0.f ? v1[e] : 0.f; v1[e] = b * b; } }
;                     u32x4 w; w.x = cvt_pk_bf16(v0[0], v0[1]); w.y = cvt_pk_bf16(v0[2], v0[3]); w.z = cvt_pk_bf16(v1[0], v1[1]); w.w = cvt_pk_bf16(v1[2], v1[3]);
;                     *(u32x4*)(rowp + bj * HALF) = w; } }
.LBB0_178:
	v_or_b32_e32 v81, 48, v140
	v_mov_b64_e32 v[82:83], s[78:79]
	v_mad_i64_i32 v[82:83], s[6:7], v81, s92, v[82:83]
	v_lshl_add_u64 v[82:83], v[142:143], 1, v[82:83]
	v_pk_mul_f32 v[78:79], v[78:79], v[80:81] op_sel_hi:[1,0]
	v_pk_mul_f32 v[76:77], v[76:77], v[80:81] op_sel_hi:[1,0]
	v_pk_mul_f32 v[84:85], v[74:75], v[80:81] op_sel_hi:[1,0]
	v_pk_mul_f32 v[74:75], v[72:73], v[80:81] op_sel_hi:[1,0]
	v_cvt_pk_bf16_f32 v72, v76, v77
	v_cvt_pk_bf16_f32 v73, v78, v79
	v_pk_mul_f32 v[68:69], v[68:69], v[80:81] op_sel_hi:[1,0]
	v_cvt_pk_bf16_f32 v74, v74, v75
	v_cvt_pk_bf16_f32 v75, v84, v85
	global_store_dwordx4 v[82:83], v[72:75], off
	v_pk_mul_f32 v[70:71], v[70:71], v[80:81] op_sel_hi:[1,0]
	s_and_b64 vcc, exec, s[4:5]
	v_pk_mul_f32 v[72:73], v[66:67], v[80:81] op_sel_hi:[1,0]
	v_pk_mul_f32 v[66:67], v[64:65], v[80:81] op_sel_hi:[1,0]
	v_cvt_pk_bf16_f32 v64, v68, v69
	v_cvt_pk_bf16_f32 v65, v70, v71
	s_nop 0
	v_cvt_pk_bf16_f32 v66, v66, v67
	v_cvt_pk_bf16_f32 v67, v72, v73
	global_store_dwordx4 v[82:83], v[64:67], off offset:256
	s_nop 1
	v_mov_b32_e32 v64, v138
	s_cbranch_vccnz .LBB0_180
	s_waitcnt vmcnt(11)
	s_nop 0
	v_mov_b32_e32 v64, v164
	v_mov_b32_e32 v65, v165
	v_ffbh_u32_e32 v66, v65
	v_min_u32_e32 v66, 32, v66
	v_lshlrev_b64 v[64:65], v66, v[64:65]
	v_min_u32_e32 v64, 1, v64
	v_or_b32_e32 v64, v65, v64
	v_cvt_f32_u32_e32 v64, v64
	v_sub_u32_e32 v65, 32, v66
	v_ldexp_f32 v64, v64, v65
	v_fmamk_f32 v64, v64, 0x30000000, v208
	v_mul_f32_e32 v65, 0x4f800000, v64
	v_cmp_gt_f32_e32 vcc, s33, v64
	s_nop 1
	v_cndmask_b32_e32 v64, v64, v65, vcc
	v_sqrt_f32_e32 v65, v64
	s_nop 0
	v_add_u32_e32 v66, -1, v65
	v_add_u32_e32 v67, 1, v65
	v_fma_f32 v68, -v66, v65, v64
	v_fma_f32 v69, -v67, v65, v64
	v_cmp_ge_f32_e64 s[6:7], 0, v68
	s_nop 1
	v_cndmask_b32_e64 v65, v65, v66, s[6:7]
	v_cmp_lt_f32_e64 s[6:7], 0, v69
	s_nop 1
	v_cndmask_b32_e64 v65, v65, v67, s[6:7]
	v_mul_f32_e32 v66, 0x37800000, v65
	v_cndmask_b32_e32 v65, v65, v66, vcc
	v_cmp_class_f32_e32 vcc, v64, v209
	s_nop 1
	v_cndmask_b32_e32 v64, v65, v64, vcc
	v_div_scale_f32 v65, s[6:7], v64, v64, 1.0
	v_rcp_f32_e32 v66, v65
	v_div_scale_f32 v67, vcc, 1.0, v64, 1.0
	v_fma_f32 v68, -v65, v66, 1.0
	v_fmac_f32_e32 v66, v68, v66
	v_mul_f32_e32 v68, v67, v66
	v_fma_f32 v69, -v65, v68, v67
	v_fmac_f32_e32 v68, v69, v66
	v_fma_f32 v65, -v65, v68, v67
	v_div_fmas_f32 v65, v65, v66, v68
	v_div_fixup_f32 v64, v65, v64, 1.0
	v_mul_f32_e32 v64, v138, v64
.LBB0_180:
	v_add_u32_e32 v65, 0x80, v140
	v_mov_b64_e32 v[66:67], s[78:79]
	v_mad_i64_i32 v[66:67], s[6:7], v65, s92, v[66:67]
	v_lshl_add_u64 v[66:67], v[142:143], 1, v[66:67]
	v_pk_mul_f32 v[62:63], v[62:63], v[64:65] op_sel_hi:[1,0]
	v_pk_mul_f32 v[60:61], v[60:61], v[64:65] op_sel_hi:[1,0]
	v_pk_mul_f32 v[68:69], v[58:59], v[64:65] op_sel_hi:[1,0]
	v_pk_mul_f32 v[58:59], v[56:57], v[64:65] op_sel_hi:[1,0]
	v_cvt_pk_bf16_f32 v56, v60, v61
	v_cvt_pk_bf16_f32 v57, v62, v63
	v_pk_mul_f32 v[52:53], v[52:53], v[64:65] op_sel_hi:[1,0]
	v_cvt_pk_bf16_f32 v58, v58, v59
	v_cvt_pk_bf16_f32 v59, v68, v69
	global_store_dwordx4 v[66:67], v[56:59], off
	v_pk_mul_f32 v[54:55], v[54:55], v[64:65] op_sel_hi:[1,0]
	s_and_b64 vcc, exec, s[4:5]
	v_pk_mul_f32 v[56:57], v[50:51], v[64:65] op_sel_hi:[1,0]
	v_pk_mul_f32 v[50:51], v[48:49], v[64:65] op_sel_hi:[1,0]
	v_cvt_pk_bf16_f32 v48, v52, v53
	v_cvt_pk_bf16_f32 v49, v54, v55
	s_nop 0
	v_cvt_pk_bf16_f32 v50, v50, v51
	v_cvt_pk_bf16_f32 v51, v56, v57
	global_store_dwordx4 v[66:67], v[48:51], off offset:256
	s_nop 1
	v_mov_b32_e32 v48, v138
	s_cbranch_vccnz .LBB0_182
	s_waitcnt vmcnt(12)
	s_nop 0
	v_mov_b32_e32 v48, v166
	v_mov_b32_e32 v49, v167
	v_ffbh_u32_e32 v50, v49
	v_min_u32_e32 v50, 32, v50
	v_lshlrev_b64 v[48:49], v50, v[48:49]
	v_min_u32_e32 v48, 1, v48
	v_or_b32_e32 v48, v49, v48
	v_cvt_f32_u32_e32 v48, v48
	v_sub_u32_e32 v49, 32, v50
	v_ldexp_f32 v48, v48, v49
	v_fmamk_f32 v48, v48, 0x30000000, v208
	v_mul_f32_e32 v49, 0x4f800000, v48
	v_cmp_gt_f32_e32 vcc, s33, v48
	s_nop 1
	v_cndmask_b32_e32 v48, v48, v49, vcc
	v_sqrt_f32_e32 v49, v48
	s_nop 0
	v_add_u32_e32 v50, -1, v49
	v_add_u32_e32 v51, 1, v49
	v_fma_f32 v52, -v50, v49, v48
	v_fma_f32 v53, -v51, v49, v48
	v_cmp_ge_f32_e64 s[6:7], 0, v52
	s_nop 1
	v_cndmask_b32_e64 v49, v49, v50, s[6:7]
	v_cmp_lt_f32_e64 s[6:7], 0, v53
	s_nop 1
	v_cndmask_b32_e64 v49, v49, v51, s[6:7]
	v_mul_f32_e32 v50, 0x37800000, v49
	v_cndmask_b32_e32 v49, v49, v50, vcc
	v_cmp_class_f32_e32 vcc, v48, v209
	s_nop 1
	v_cndmask_b32_e32 v48, v49, v48, vcc
	v_div_scale_f32 v49, s[6:7], v48, v48, 1.0
	v_rcp_f32_e32 v50, v49
	v_div_scale_f32 v51, vcc, 1.0, v48, 1.0
	v_fma_f32 v52, -v49, v50, 1.0
	v_fmac_f32_e32 v50, v52, v50
	v_mul_f32_e32 v52, v51, v50
	v_fma_f32 v53, -v49, v52, v51
	v_fmac_f32_e32 v52, v53, v50
	v_fma_f32 v49, -v49, v52, v51
	v_div_fmas_f32 v49, v49, v50, v52
	v_div_fixup_f32 v48, v49, v48, 1.0
	v_mul_f32_e32 v48, v138, v48
; __device__ __forceinline__ unsigned cvt_pk_bf16(float lo, float hi) { unsigned r; asm volatile("v_cvt_pk_bf16_f32 %0, %1, %2" : "=v"(r) : "v"(lo), "v"(hi)); return r; }
;     __device__ __forceinline__ void operator()(const f32x4 (&acc)[2][2][4][2], const Unit& u, int wr, int wc, int fr, int fq) const {
;     ...
;             for (int m = 0; m < 4; ++m) { bf16_t* rowp = O + (size_t)(row0 + ai * HALF + m * 16) * ldc + col0;
;                 const float rs = rowss ? sc * (1.0f / sqrtf((float)__hip_atomic_load(rowss + row0 + ai * HALF + m * 16, __ATOMIC_RELAXED, __HIP_MEMORY_SCOPE_AGENT) * (1.0f / (2048.0f * 1048576.0f)) + 1e-6f)) : sc;
; #pragma unroll
;                 for (int bj = 0; bj < 2; ++bj) { f32x4 v0 = acc[ai][bj][m][0] * rs, v1 = acc[ai][bj][m][1] * rs;
;                     if (ACT == 1) {
; #pragma unroll
;                         for (int e = 0; e < 4; ++e) { float a = v0[e] > 0.f ? v0[e] : 0.f; v0[e] = a * a; float b = v1[e] > 0.f ? v1[e] : 0.f; v1[e] = b * b; } }
;                     u32x4 w; w.x = cvt_pk_bf16(v0[0], v0[1]); w.y = cvt_pk_bf16(v0[2], v0[3]); w.z = cvt_pk_bf16(v1[0], v1[1]); w.w = cvt_pk_bf16(v1[2], v1[3]);
;                     *(u32x4*)(rowp + bj * HALF) = w; } }
.LBB0_182:
	v_add_u32_e32 v49, 0x90, v140
	v_mov_b64_e32 v[50:51], s[78:79]
	v_mad_i64_i32 v[50:51], s[6:7], v49, s92, v[50:51]
	v_lshl_add_u64 v[50:51], v[142:143], 1, v[50:51]
	v_pk_mul_f32 v[46:47], v[46:47], v[48:49] op_sel_hi:[1,0]
	v_pk_mul_f32 v[44:45], v[44:45], v[48:49] op_sel_hi:[1,0]
	v_pk_mul_f32 v[52:53], v[42:43], v[48:49] op_sel_hi:[1,0]
	v_pk_mul_f32 v[42:43], v[40:41], v[48:49] op_sel_hi:[1,0]
	v_cvt_pk_bf16_f32 v40, v44, v45
	v_cvt_pk_bf16_f32 v41, v46, v47
	v_pk_mul_f32 v[36:37], v[36:37], v[48:49] op_sel_hi:[1,0]
	v_cvt_pk_bf16_f32 v42, v42, v43
	v_cvt_pk_bf16_f32 v43, v52, v53
	global_store_dwordx4 v[50:51], v[40:43], off
	v_pk_mul_f32 v[38:39], v[38:39], v[48:49] op_sel_hi:[1,0]
	s_and_b64 vcc, exec, s[4:5]
	v_pk_mul_f32 v[40:41], v[34:35], v[48:49] op_sel_hi:[1,0]
	v_pk_mul_f32 v[34:35], v[32:33], v[48:49] op_sel_hi:[1,0]
	v_cvt_pk_bf16_f32 v32, v36, v37
	v_cvt_pk_bf16_f32 v33, v38, v39
	s_nop 0
	v_cvt_pk_bf16_f32 v34, v34, v35
	v_cvt_pk_bf16_f32 v35, v40, v41
	global_store_dwordx4 v[50:51], v[32:35], off offset:256
	s_nop 1
	v_mov_b32_e32 v32, v138
	s_cbranch_vccnz .LBB0_184
	s_waitcnt vmcnt(13)
	s_nop 0
	v_mov_b32_e32 v32, v168
	v_mov_b32_e32 v33, v169
	v_ffbh_u32_e32 v34, v33
	v_min_u32_e32 v34, 32, v34
	v_lshlrev_b64 v[32:33], v34, v[32:33]
	v_min_u32_e32 v32, 1, v32
	v_or_b32_e32 v32, v33, v32
	v_cvt_f32_u32_e32 v32, v32
	v_sub_u32_e32 v33, 32, v34
	v_ldexp_f32 v32, v32, v33
	v_fmamk_f32 v32, v32, 0x30000000, v208
	v_mul_f32_e32 v33, 0x4f800000, v32
	v_cmp_gt_f32_e32 vcc, s33, v32
	s_nop 1
	v_cndmask_b32_e32 v32, v32, v33, vcc
	v_sqrt_f32_e32 v33, v32
	s_nop 0
	v_add_u32_e32 v34, -1, v33
	v_add_u32_e32 v35, 1, v33
	v_fma_f32 v36, -v34, v33, v32
	v_fma_f32 v37, -v35, v33, v32
	v_cmp_ge_f32_e64 s[6:7], 0, v36
	s_nop 1
	v_cndmask_b32_e64 v33, v33, v34, s[6:7]
	v_cmp_lt_f32_e64 s[6:7], 0, v37
	s_nop 1
	v_cndmask_b32_e64 v33, v33, v35, s[6:7]
	v_mul_f32_e32 v34, 0x37800000, v33
	v_cndmask_b32_e32 v33, v33, v34, vcc
	v_cmp_class_f32_e32 vcc, v32, v209
	s_nop 1
	v_cndmask_b32_e32 v32, v33, v32, vcc
	v_div_scale_f32 v33, s[6:7], v32, v32, 1.0
	v_rcp_f32_e32 v34, v33
	v_div_scale_f32 v35, vcc, 1.0, v32, 1.0
	v_fma_f32 v36, -v33, v34, 1.0
	v_fmac_f32_e32 v34, v36, v34
	v_mul_f32_e32 v36, v35, v34
	v_fma_f32 v37, -v33, v36, v35
	v_fmac_f32_e32 v36, v37, v34
	v_fma_f32 v33, -v33, v36, v35
	v_div_fmas_f32 v33, v33, v34, v36
	v_div_fixup_f32 v32, v33, v32, 1.0
	v_mul_f32_e32 v32, v138, v32
.LBB0_184:
	v_add_u32_e32 v33, 0xa0, v140
	v_mov_b64_e32 v[34:35], s[78:79]
	v_mad_i64_i32 v[34:35], s[6:7], v33, s92, v[34:35]
	v_lshl_add_u64 v[34:35], v[142:143], 1, v[34:35]
	v_pk_mul_f32 v[30:31], v[30:31], v[32:33] op_sel_hi:[1,0]
	v_pk_mul_f32 v[28:29], v[28:29], v[32:33] op_sel_hi:[1,0]
	v_pk_mul_f32 v[36:37], v[26:27], v[32:33] op_sel_hi:[1,0]
	v_pk_mul_f32 v[26:27], v[24:25], v[32:33] op_sel_hi:[1,0]
	v_cvt_pk_bf16_f32 v24, v28, v29
	v_cvt_pk_bf16_f32 v25, v30, v31
	s_and_b64 vcc, exec, s[4:5]
	v_cvt_pk_bf16_f32 v26, v26, v27
	v_cvt_pk_bf16_f32 v27, v36, v37
	global_store_dwordx4 v[34:35], v[24:27], off
	v_pk_mul_f32 v[22:23], v[22:23], v[32:33] op_sel_hi:[1,0]
	v_pk_mul_f32 v[20:21], v[20:21], v[32:33] op_sel_hi:[1,0]
	v_pk_mul_f32 v[24:25], v[18:19], v[32:33] op_sel_hi:[1,0]
	v_pk_mul_f32 v[18:19], v[16:17], v[32:33] op_sel_hi:[1,0]
	v_cvt_pk_bf16_f32 v16, v20, v21
	v_cvt_pk_bf16_f32 v17, v22, v23
	s_nop 0
	v_cvt_pk_bf16_f32 v18, v18, v19
	v_cvt_pk_bf16_f32 v19, v24, v25
	global_store_dwordx4 v[34:35], v[16:19], off offset:256
	s_cbranch_vccnz .LBB0_186
	s_waitcnt vmcnt(14)
	s_nop 0
	v_mov_b32_e32 v16, v170
	v_mov_b32_e32 v17, v171
	v_ffbh_u32_e32 v18, v17
	v_min_u32_e32 v18, 32, v18
	v_lshlrev_b64 v[16:17], v18, v[16:17]
	v_min_u32_e32 v16, 1, v16
	v_or_b32_e32 v16, v17, v16
	v_cvt_f32_u32_e32 v16, v16
	v_sub_u32_e32 v17, 32, v18
	v_ldexp_f32 v16, v16, v17
	v_fmamk_f32 v16, v16, 0x30000000, v208
	v_mul_f32_e32 v17, 0x4f800000, v16
	v_cmp_gt_f32_e32 vcc, s33, v16
	s_nop 1
	v_cndmask_b32_e32 v16, v16, v17, vcc
	v_sqrt_f32_e32 v17, v16
	s_nop 0
	v_add_u32_e32 v18, -1, v17
	v_add_u32_e32 v19, 1, v17
	v_fma_f32 v20, -v18, v17, v16
	v_fma_f32 v21, -v19, v17, v16
	v_cmp_ge_f32_e64 s[4:5], 0, v20
	s_nop 1
	v_cndmask_b32_e64 v17, v17, v18, s[4:5]
	v_cmp_lt_f32_e64 s[4:5], 0, v21
	s_nop 1
	v_cndmask_b32_e64 v17, v17, v19, s[4:5]
	v_mul_f32_e32 v18, 0x37800000, v17
	v_cndmask_b32_e32 v17, v17, v18, vcc
	v_cmp_class_f32_e32 vcc, v16, v209
	s_nop 1
	v_cndmask_b32_e32 v16, v17, v16, vcc
	v_div_scale_f32 v17, s[4:5], v16, v16, 1.0
	v_rcp_f32_e32 v18, v17
	v_div_scale_f32 v19, vcc, 1.0, v16, 1.0
	v_fma_f32 v20, -v17, v18, 1.0
	v_fmac_f32_e32 v18, v20, v18
	v_mul_f32_e32 v20, v19, v18
	v_fma_f32 v21, -v17, v20, v19
	v_fmac_f32_e32 v20, v21, v18
	v_fma_f32 v17, -v17, v20, v19
	v_div_fmas_f32 v17, v17, v18, v20
	v_div_fixup_f32 v16, v17, v16, 1.0
	v_mul_f32_e32 v138, v138, v16

; __device__ __forceinline__ unsigned cvt_pk_bf16(float lo, float hi) { unsigned r; asm volatile("v_cvt_pk_bf16_f32 %0, %1, %2" : "=v"(r) : "v"(lo), "v"(hi)); return r; }
;     __device__ __forceinline__ void operator()(const f32x4 (&acc)[2][2][4][2], const Unit& u, int wr, int wc, int fr, int fq) const {
;     ...
;             for (int m = 0; m < 4; ++m) { bf16_t* rowp = O + (size_t)(row0 + ai * HALF + m * 16) * ldc + col0;
;                 const float rs = rowss ? sc * (1.0f / sqrtf((float)__hip_atomic_load(rowss + row0 + ai * HALF + m * 16, __ATOMIC_RELAXED, __HIP_MEMORY_SCOPE_AGENT) * (1.0f / (2048.0f * 1048576.0f)) + 1e-6f)) : sc;
; #pragma unroll
;                 for (int bj = 0; bj < 2; ++bj) { f32x4 v0 = acc[ai][bj][m][0] * rs, v1 = acc[ai][bj][m][1] * rs;
;                     if (ACT == 1) {
; #pragma unroll
;                         for (int e = 0; e < 4; ++e) { float a = v0[e] > 0.f ? v0[e] : 0.f; v0[e] = a * a; float b = v1[e] > 0.f ? v1[e] : 0.f; v1[e] = b * b; } }
;                     u32x4 w; w.x = cvt_pk_bf16(v0[0], v0[1]); w.y = cvt_pk_bf16(v0[2], v0[3]); w.z = cvt_pk_bf16(v1[0], v1[1]); w.w = cvt_pk_bf16(v1[2], v1[3]);
;                     *(u32x4*)(rowp + bj * HALF) = w; } }
.LBB0_1215:
	v_lshl_add_u32 v144, s42, 8, v146
	v_ashrrev_i32_e32 v145, 31, v144
	v_lshl_add_u64 v[140:141], v[144:145], 3, s[2:3]
	global_load_dwordx2 v[156:157], v[140:141], off sc1
	global_load_dwordx2 v[158:159], v[140:141], off offset:128 sc1
	global_load_dwordx2 v[160:161], v[140:141], off offset:256 sc1
	global_load_dwordx2 v[162:163], v[140:141], off offset:384 sc1
	global_load_dwordx2 v[164:165], v[140:141], off offset:1024 sc1
	global_load_dwordx2 v[166:167], v[140:141], off offset:1152 sc1
	global_load_dwordx2 v[168:169], v[140:141], off offset:1280 sc1
	global_load_dwordx2 v[170:171], v[140:141], off offset:1408 sc1
	v_lshlrev_b64 v[150:151], 14, v[144:145]
	s_waitcnt vmcnt(7)
	v_mov_b32_e32 v138, v156
	v_mov_b32_e32 v139, v157
	v_ffbh_u32_e32 v142, v139
	v_min_u32_e32 v142, 32, v142
	v_lshlrev_b64 v[138:139], v142, v[138:139]
	v_min_u32_e32 v138, 1, v138
	v_or_b32_e32 v138, v139, v138
	v_cvt_f32_u32_e32 v143, v138
	v_sub_u32_e32 v142, 32, v142
	v_lshl_or_b32 v138, s41, 8, v148
	v_ashrrev_i32_e32 v139, 31, v138
	v_ldexp_f32 v142, v143, v142
	v_fmamk_f32 v142, v142, 0x30000000, v208
	v_mul_f32_e32 v143, 0x4f800000, v142
	v_cmp_gt_f32_e32 vcc, s33, v142
	s_nop 1
	v_cndmask_b32_e32 v152, v142, v143, vcc
	v_sqrt_f32_e32 v153, v152
	v_lshlrev_b64 v[142:143], 1, v[138:139]
	v_lshl_add_u64 v[138:139], s[78:79], 0, v[150:151]
	v_lshl_add_u64 v[138:139], v[138:139], 0, v[142:143]
	v_add_u32_e32 v145, -1, v153
	v_add_u32_e32 v150, 1, v153
	v_fma_f32 v151, -v145, v153, v152
	v_fma_f32 v154, -v150, v153, v152
	v_cmp_ge_f32_e64 s[4:5], 0, v151
	s_nop 1
	v_cndmask_b32_e64 v145, v153, v145, s[4:5]
	v_cmp_lt_f32_e64 s[4:5], 0, v154
	s_nop 1
	v_cndmask_b32_e64 v145, v145, v150, s[4:5]
	v_mul_f32_e32 v150, 0x37800000, v145
	v_cndmask_b32_e32 v145, v145, v150, vcc
	v_cmp_class_f32_e32 vcc, v152, v209
	s_nop 1
	v_cndmask_b32_e32 v145, v145, v152, vcc
	v_div_scale_f32 v150, s[4:5], v145, v145, 1.0
	v_rcp_f32_e32 v151, v150
	v_div_scale_f32 v152, vcc, 1.0, v145, 1.0
	v_fma_f32 v153, -v150, v151, 1.0
	v_fmac_f32_e32 v151, v153, v151
	v_mul_f32_e32 v153, v152, v151
	v_fma_f32 v154, -v150, v153, v152
	v_fmac_f32_e32 v153, v154, v151
	v_fma_f32 v150, -v150, v153, v152
	v_div_fmas_f32 v150, v150, v151, v153
	v_div_fixup_f32 v150, v150, v145, 1.0
	v_pk_mul_f32 v[126:127], v[126:127], v[150:151] op_sel_hi:[1,0]
	v_pk_mul_f32 v[124:125], v[124:125], v[150:151] op_sel_hi:[1,0]
	v_pk_mul_f32 v[122:123], v[122:123], v[150:151] op_sel_hi:[1,0]
	v_pk_mul_f32 v[120:121], v[120:121], v[150:151] op_sel_hi:[1,0]
	v_pk_mul_f32 v[114:115], v[114:115], v[150:151] op_sel_hi:[1,0]
	v_pk_mul_f32 v[112:113], v[112:113], v[150:151] op_sel_hi:[1,0]
	v_pk_mul_f32 v[118:119], v[118:119], v[150:151] op_sel_hi:[1,0]
	v_pk_mul_f32 v[116:117], v[116:117], v[150:151] op_sel_hi:[1,0]
	v_max_f32_e32 v124, 0, v124
	v_max_f32_e32 v120, 0, v120
	v_max_f32_e32 v125, 0, v125
	v_max_f32_e32 v121, 0, v121
	v_max_f32_e32 v126, 0, v126
	v_max_f32_e32 v122, 0, v122
	v_max_f32_e32 v127, 0, v127
	v_max_f32_e32 v123, 0, v123
	v_max_f32_e32 v112, 0, v112
	v_max_f32_e32 v113, 0, v113
	v_max_f32_e32 v114, 0, v114
	v_max_f32_e32 v115, 0, v115
	v_max_f32_e32 v116, 0, v116
	v_max_f32_e32 v117, 0, v117
	v_max_f32_e32 v118, 0, v118
	v_max_f32_e32 v119, 0, v119
	v_mul_f32_e32 v124, v124, v124
	v_mul_f32_e32 v120, v120, v120
	v_mul_f32_e32 v125, v125, v125
	v_mul_f32_e32 v121, v121, v121
	v_mul_f32_e32 v126, v126, v126
	v_mul_f32_e32 v122, v122, v122
	v_mul_f32_e32 v127, v127, v127
	v_mul_f32_e32 v123, v123, v123
	v_mul_f32_e32 v145, v112, v112
	v_mul_f32_e32 v150, v113, v113
	v_mul_f32_e32 v151, v114, v114
	v_mul_f32_e32 v152, v115, v115
	v_cvt_pk_bf16_f32 v112, v124, v125
	v_cvt_pk_bf16_f32 v113, v126, v127
	v_cvt_pk_bf16_f32 v114, v120, v121
	v_cvt_pk_bf16_f32 v115, v122, v123
	v_mul_f32_e32 v116, v116, v116
	v_mul_f32_e32 v117, v117, v117
	v_mul_f32_e32 v118, v118, v118
	v_mul_f32_e32 v119, v119, v119
	global_store_dwordx4 v[138:139], v[112:115], off
	s_nop 1
	v_cvt_pk_bf16_f32 v112, v116, v117
	v_cvt_pk_bf16_f32 v113, v118, v119
	v_cvt_pk_bf16_f32 v114, v145, v150
	v_cvt_pk_bf16_f32 v115, v151, v152
	global_store_dwordx4 v[138:139], v[112:115], off offset:256
	s_waitcnt vmcnt(8)
	s_nop 0
	v_mov_b32_e32 v112, v158
	v_mov_b32_e32 v113, v159
	v_ffbh_u32_e32 v114, v113
	v_min_u32_e32 v114, 32, v114
	v_lshlrev_b64 v[112:113], v114, v[112:113]
	v_min_u32_e32 v112, 1, v112
	v_or_b32_e32 v112, v113, v112
	v_cvt_f32_u32_e32 v113, v112
	v_sub_u32_e32 v114, 32, v114
	v_or_b32_e32 v112, 16, v144
	v_ldexp_f32 v113, v113, v114
	v_fmamk_f32 v113, v113, 0x30000000, v208
	v_mul_f32_e32 v114, 0x4f800000, v113
	v_cmp_gt_f32_e32 vcc, s33, v113
	s_nop 1
	v_cndmask_b32_e32 v114, v113, v114, vcc
	v_sqrt_f32_e32 v115, v114
	v_ashrrev_i32_e32 v113, 31, v112
	v_lshlrev_b64 v[112:113], 14, v[112:113]
	v_lshl_add_u64 v[112:113], s[78:79], 0, v[112:113]
	v_add_u32_e32 v116, -1, v115
	v_add_u32_e32 v117, 1, v115
	v_fma_f32 v118, -v116, v115, v114
	v_fma_f32 v119, -v117, v115, v114
	v_cmp_ge_f32_e64 s[4:5], 0, v118
	v_lshl_add_u64 v[112:113], v[112:113], 0, v[142:143]
	s_nop 0
	v_cndmask_b32_e64 v115, v115, v116, s[4:5]
	v_cmp_lt_f32_e64 s[4:5], 0, v119
	s_nop 1
	v_cndmask_b32_e64 v115, v115, v117, s[4:5]
	v_mul_f32_e32 v116, 0x37800000, v115
	v_cndmask_b32_e32 v115, v115, v116, vcc
	v_cmp_class_f32_e32 vcc, v114, v209
	s_nop 1
	v_cndmask_b32_e32 v114, v115, v114, vcc
	v_div_scale_f32 v115, s[4:5], v114, v114, 1.0
	v_rcp_f32_e32 v116, v115
	v_div_scale_f32 v117, vcc, 1.0, v114, 1.0
	v_fma_f32 v118, -v115, v116, 1.0
	v_fmac_f32_e32 v116, v118, v116
	v_mul_f32_e32 v118, v117, v116
	v_fma_f32 v119, -v115, v118, v117
; __device__ __forceinline__ unsigned cvt_pk_bf16(float lo, float hi) { unsigned r; asm volatile("v_cvt_pk_bf16_f32 %0, %1, %2" : "=v"(r) : "v"(lo), "v"(hi)); return r; }
;     __device__ __forceinline__ void operator()(const f32x4 (&acc)[2][2][4][2], const Unit& u, int wr, int wc, int fr, int fq) const {
;     ...
;             for (int m = 0; m < 4; ++m) { bf16_t* rowp = O + (size_t)(row0 + ai * HALF + m * 16) * ldc + col0;
;                 const float rs = rowss ? sc * (1.0f / sqrtf((float)__hip_atomic_load(rowss + row0 + ai * HALF + m * 16, __ATOMIC_RELAXED, __HIP_MEMORY_SCOPE_AGENT) * (1.0f / (2048.0f * 1048576.0f)) + 1e-6f)) : sc;
; #pragma unroll
;                 for (int bj = 0; bj < 2; ++bj) { f32x4 v0 = acc[ai][bj][m][0] * rs, v1 = acc[ai][bj][m][1] * rs;
;                     if (ACT == 1) {
; #pragma unroll
;                         for (int e = 0; e < 4; ++e) { float a = v0[e] > 0.f ? v0[e] : 0.f; v0[e] = a * a; float b = v1[e] > 0.f ? v1[e] : 0.f; v1[e] = b * b; } }
;                     u32x4 w; w.x = cvt_pk_bf16(v0[0], v0[1]); w.y = cvt_pk_bf16(v0[2], v0[3]); w.z = cvt_pk_bf16(v1[0], v1[1]); w.w = cvt_pk_bf16(v1[2], v1[3]);
;                     *(u32x4*)(rowp + bj * HALF) = w; } }
	v_fmac_f32_e32 v118, v119, v116
	v_fma_f32 v115, -v115, v118, v117
	v_div_fmas_f32 v115, v115, v116, v118
	v_div_fixup_f32 v114, v115, v114, 1.0
	v_pk_mul_f32 v[110:111], v[110:111], v[114:115] op_sel_hi:[1,0]
	v_pk_mul_f32 v[108:109], v[108:109], v[114:115] op_sel_hi:[1,0]
	v_pk_mul_f32 v[106:107], v[106:107], v[114:115] op_sel_hi:[1,0]
	v_pk_mul_f32 v[104:105], v[104:105], v[114:115] op_sel_hi:[1,0]
	v_pk_mul_f32 v[98:99], v[98:99], v[114:115] op_sel_hi:[1,0]
	v_pk_mul_f32 v[96:97], v[96:97], v[114:115] op_sel_hi:[1,0]
	v_pk_mul_f32 v[102:103], v[102:103], v[114:115] op_sel_hi:[1,0]
	v_pk_mul_f32 v[100:101], v[100:101], v[114:115] op_sel_hi:[1,0]
	v_max_f32_e32 v108, 0, v108
	v_max_f32_e32 v104, 0, v104
	v_max_f32_e32 v109, 0, v109
	v_max_f32_e32 v105, 0, v105
	v_max_f32_e32 v110, 0, v110
	v_max_f32_e32 v106, 0, v106
	v_max_f32_e32 v111, 0, v111
	v_max_f32_e32 v107, 0, v107
	v_max_f32_e32 v96, 0, v96
	v_max_f32_e32 v97, 0, v97
	v_max_f32_e32 v98, 0, v98
	v_max_f32_e32 v99, 0, v99
	v_max_f32_e32 v100, 0, v100
	v_max_f32_e32 v101, 0, v101
	v_max_f32_e32 v102, 0, v102
	v_max_f32_e32 v103, 0, v103
	v_mul_f32_e32 v108, v108, v108
	v_mul_f32_e32 v104, v104, v104
	v_mul_f32_e32 v109, v109, v109
	v_mul_f32_e32 v105, v105, v105
	v_mul_f32_e32 v110, v110, v110
	v_mul_f32_e32 v106, v106, v106
	v_mul_f32_e32 v111, v111, v111
	v_mul_f32_e32 v107, v107, v107
	v_mul_f32_e32 v114, v96, v96
	v_mul_f32_e32 v115, v97, v97
	v_mul_f32_e32 v116, v98, v98
	v_mul_f32_e32 v117, v99, v99
	v_cvt_pk_bf16_f32 v96, v108, v109
	v_cvt_pk_bf16_f32 v97, v110, v111
	v_cvt_pk_bf16_f32 v98, v104, v105
	v_cvt_pk_bf16_f32 v99, v106, v107
	v_mul_f32_e32 v100, v100, v100
	v_mul_f32_e32 v101, v101, v101
	v_mul_f32_e32 v102, v102, v102
	v_mul_f32_e32 v103, v103, v103
	global_store_dwordx4 v[112:113], v[96:99], off
	s_nop 1
	v_cvt_pk_bf16_f32 v96, v100, v101
	v_cvt_pk_bf16_f32 v97, v102, v103
	v_cvt_pk_bf16_f32 v98, v114, v115
	v_cvt_pk_bf16_f32 v99, v116, v117
	global_store_dwordx4 v[112:113], v[96:99], off offset:256
	s_waitcnt vmcnt(9)
	s_nop 0
	v_mov_b32_e32 v96, v160
	v_mov_b32_e32 v97, v161
	v_ffbh_u32_e32 v98, v97
	v_min_u32_e32 v98, 32, v98
	v_lshlrev_b64 v[96:97], v98, v[96:97]
	v_min_u32_e32 v96, 1, v96
	v_or_b32_e32 v96, v97, v96
	v_cvt_f32_u32_e32 v97, v96
	v_sub_u32_e32 v98, 32, v98
	v_or_b32_e32 v96, 32, v144
	v_ldexp_f32 v97, v97, v98
	v_fmamk_f32 v97, v97, 0x30000000, v208
	v_mul_f32_e32 v98, 0x4f800000, v97
	v_cmp_gt_f32_e32 vcc, s33, v97
	s_nop 1
	v_cndmask_b32_e32 v98, v97, v98, vcc
	v_sqrt_f32_e32 v99, v98
	v_ashrrev_i32_e32 v97, 31, v96
	v_lshlrev_b64 v[96:97], 14, v[96:97]
	v_lshl_add_u64 v[96:97], s[78:79], 0, v[96:97]
	v_add_u32_e32 v100, -1, v99
	v_add_u32_e32 v101, 1, v99
	v_fma_f32 v102, -v100, v99, v98
	v_fma_f32 v103, -v101, v99, v98
	v_cmp_ge_f32_e64 s[4:5], 0, v102
	v_lshl_add_u64 v[96:97], v[96:97], 0, v[142:143]
	s_nop 0
	v_cndmask_b32_e64 v99, v99, v100, s[4:5]
	v_cmp_lt_f32_e64 s[4:5], 0, v103
	s_nop 1
	v_cndmask_b32_e64 v99, v99, v101, s[4:5]
	v_mul_f32_e32 v100, 0x37800000, v99
	v_cndmask_b32_e32 v99, v99, v100, vcc
	v_cmp_class_f32_e32 vcc, v98, v209
	s_nop 1
	v_cndmask_b32_e32 v98, v99, v98, vcc
	v_div_scale_f32 v99, s[4:5], v98, v98, 1.0
	v_rcp_f32_e32 v100, v99
	v_div_scale_f32 v101, vcc, 1.0, v98, 1.0
	v_fma_f32 v102, -v99, v100, 1.0
	v_fmac_f32_e32 v100, v102, v100
	v_mul_f32_e32 v102, v101, v100
	v_fma_f32 v103, -v99, v102, v101
	v_fmac_f32_e32 v102, v103, v100
	v_fma_f32 v99, -v99, v102, v101
	v_div_fmas_f32 v99, v99, v100, v102
	v_div_fixup_f32 v98, v99, v98, 1.0
	v_pk_mul_f32 v[94:95], v[94:95], v[98:99] op_sel_hi:[1,0]
	v_pk_mul_f32 v[92:93], v[92:93], v[98:99] op_sel_hi:[1,0]
	v_pk_mul_f32 v[90:91], v[90:91], v[98:99] op_sel_hi:[1,0]
	v_pk_mul_f32 v[88:89], v[88:89], v[98:99] op_sel_hi:[1,0]
	v_pk_mul_f32 v[82:83], v[82:83], v[98:99] op_sel_hi:[1,0]
	v_pk_mul_f32 v[80:81], v[80:81], v[98:99] op_sel_hi:[1,0]
	v_pk_mul_f32 v[86:87], v[86:87], v[98:99] op_sel_hi:[1,0]
	v_pk_mul_f32 v[84:85], v[84:85], v[98:99] op_sel_hi:[1,0]
	v_max_f32_e32 v92, 0, v92
	v_max_f32_e32 v88, 0, v88
	v_max_f32_e32 v93, 0, v93
	v_max_f32_e32 v89, 0, v89
	v_max_f32_e32 v94, 0, v94
	v_max_f32_e32 v90, 0, v90
	v_max_f32_e32 v95, 0, v95
	v_max_f32_e32 v91, 0, v91
	v_max_f32_e32 v80, 0, v80
	v_max_f32_e32 v81, 0, v81
	v_max_f32_e32 v82, 0, v82
	v_max_f32_e32 v83, 0, v83
	v_max_f32_e32 v84, 0, v84
	v_max_f32_e32 v85, 0, v85
	v_max_f32_e32 v86, 0, v86
	v_max_f32_e32 v87, 0, v87
	v_mul_f32_e32 v92, v92, v92
	v_mul_f32_e32 v88, v88, v88
	v_mul_f32_e32 v93, v93, v93
	v_mul_f32_e32 v89, v89, v89
	v_mul_f32_e32 v94, v94, v94
	v_mul_f32_e32 v90, v90, v90
	v_mul_f32_e32 v95, v95, v95
	v_mul_f32_e32 v91, v91, v91
	v_mul_f32_e32 v98, v80, v80
	v_mul_f32_e32 v99, v81, v81
	v_mul_f32_e32 v100, v82, v82
	v_mul_f32_e32 v101, v83, v83
	v_cvt_pk_bf16_f32 v80, v92, v93
	v_cvt_pk_bf16_f32 v81, v94, v95
	v_cvt_pk_bf16_f32 v82, v88, v89
	v_cvt_pk_bf16_f32 v83, v90, v91
	v_mul_f32_e32 v84, v84, v84
	v_mul_f32_e32 v85, v85, v85
	v_mul_f32_e32 v86, v86, v86
	v_mul_f32_e32 v87, v87, v87
	global_store_dwordx4 v[96:97], v[80:83], off
	s_nop 1
	v_cvt_pk_bf16_f32 v80, v84, v85
	v_cvt_pk_bf16_f32 v81, v86, v87
	v_cvt_pk_bf16_f32 v82, v98, v99
	v_cvt_pk_bf16_f32 v83, v100, v101
	global_store_dwordx4 v[96:97], v[80:83], off offset:256
	s_waitcnt vmcnt(10)
; __device__ __forceinline__ unsigned cvt_pk_bf16(float lo, float hi) { unsigned r; asm volatile("v_cvt_pk_bf16_f32 %0, %1, %2" : "=v"(r) : "v"(lo), "v"(hi)); return r; }
;     __device__ __forceinline__ void operator()(const f32x4 (&acc)[2][2][4][2], const Unit& u, int wr, int wc, int fr, int fq) const {
;     ...
;             for (int m = 0; m < 4; ++m) { bf16_t* rowp = O + (size_t)(row0 + ai * HALF + m * 16) * ldc + col0;
;                 const float rs = rowss ? sc * (1.0f / sqrtf((float)__hip_atomic_load(rowss + row0 + ai * HALF + m * 16, __ATOMIC_RELAXED, __HIP_MEMORY_SCOPE_AGENT) * (1.0f / (2048.0f * 1048576.0f)) + 1e-6f)) : sc;
; #pragma unroll
;                 for (int bj = 0; bj < 2; ++bj) { f32x4 v0 = acc[ai][bj][m][0] * rs, v1 = acc[ai][bj][m][1] * rs;
;                     if (ACT == 1) {
; #pragma unroll
;                         for (int e = 0; e < 4; ++e) { float a = v0[e] > 0.f ? v0[e] : 0.f; v0[e] = a * a; float b = v1[e] > 0.f ? v1[e] : 0.f; v1[e] = b * b; } }
;                     u32x4 w; w.x = cvt_pk_bf16(v0[0], v0[1]); w.y = cvt_pk_bf16(v0[2], v0[3]); w.z = cvt_pk_bf16(v1[0], v1[1]); w.w = cvt_pk_bf16(v1[2], v1[3]);
;                     *(u32x4*)(rowp + bj * HALF) = w; } }
	s_nop 0
	v_mov_b32_e32 v80, v162
	v_mov_b32_e32 v81, v163
	v_ffbh_u32_e32 v82, v81
	v_min_u32_e32 v82, 32, v82
	v_lshlrev_b64 v[80:81], v82, v[80:81]
	v_min_u32_e32 v80, 1, v80
	v_or_b32_e32 v80, v81, v80
	v_cvt_f32_u32_e32 v81, v80
	v_sub_u32_e32 v82, 32, v82
	v_or_b32_e32 v80, 48, v144
	v_ldexp_f32 v81, v81, v82
	v_fmamk_f32 v81, v81, 0x30000000, v208
	v_mul_f32_e32 v82, 0x4f800000, v81
	v_cmp_gt_f32_e32 vcc, s33, v81
	s_nop 1
	v_cndmask_b32_e32 v82, v81, v82, vcc
	v_sqrt_f32_e32 v83, v82
	v_ashrrev_i32_e32 v81, 31, v80
	v_lshlrev_b64 v[80:81], 14, v[80:81]
	v_lshl_add_u64 v[80:81], s[78:79], 0, v[80:81]
	v_add_u32_e32 v84, -1, v83
	v_add_u32_e32 v85, 1, v83
	v_fma_f32 v86, -v84, v83, v82
	v_fma_f32 v87, -v85, v83, v82
	v_cmp_ge_f32_e64 s[4:5], 0, v86
	v_lshl_add_u64 v[80:81], v[80:81], 0, v[142:143]
	s_nop 0
	v_cndmask_b32_e64 v83, v83, v84, s[4:5]
	v_cmp_lt_f32_e64 s[4:5], 0, v87
	s_nop 1
	v_cndmask_b32_e64 v83, v83, v85, s[4:5]
	v_mul_f32_e32 v84, 0x37800000, v83
	v_cndmask_b32_e32 v83, v83, v84, vcc
	v_cmp_class_f32_e32 vcc, v82, v209
	s_nop 1
	v_cndmask_b32_e32 v82, v83, v82, vcc
	v_div_scale_f32 v83, s[4:5], v82, v82, 1.0
	v_rcp_f32_e32 v84, v83
	v_div_scale_f32 v85, vcc, 1.0, v82, 1.0
	s_mov_b64 s[4:5], 0x200000
	v_fma_f32 v86, -v83, v84, 1.0
	v_fmac_f32_e32 v84, v86, v84
	v_mul_f32_e32 v86, v85, v84
	v_fma_f32 v87, -v83, v86, v85
	v_fmac_f32_e32 v86, v87, v84
	v_fma_f32 v83, -v83, v86, v85
	v_div_fmas_f32 v83, v83, v84, v86
	v_div_fixup_f32 v82, v83, v82, 1.0
	v_pk_mul_f32 v[78:79], v[78:79], v[82:83] op_sel_hi:[1,0]
	v_pk_mul_f32 v[76:77], v[76:77], v[82:83] op_sel_hi:[1,0]
	v_pk_mul_f32 v[74:75], v[74:75], v[82:83] op_sel_hi:[1,0]
	v_pk_mul_f32 v[72:73], v[72:73], v[82:83] op_sel_hi:[1,0]
	v_pk_mul_f32 v[66:67], v[66:67], v[82:83] op_sel_hi:[1,0]
	v_pk_mul_f32 v[64:65], v[64:65], v[82:83] op_sel_hi:[1,0]
	v_pk_mul_f32 v[70:71], v[70:71], v[82:83] op_sel_hi:[1,0]
	v_pk_mul_f32 v[68:69], v[68:69], v[82:83] op_sel_hi:[1,0]
	v_max_f32_e32 v76, 0, v76
	v_max_f32_e32 v72, 0, v72
	v_max_f32_e32 v77, 0, v77
	v_max_f32_e32 v73, 0, v73
	v_max_f32_e32 v78, 0, v78
	v_max_f32_e32 v74, 0, v74
	v_max_f32_e32 v79, 0, v79
	v_max_f32_e32 v75, 0, v75
	v_max_f32_e32 v64, 0, v64
	v_max_f32_e32 v65, 0, v65
	v_max_f32_e32 v66, 0, v66
	v_max_f32_e32 v67, 0, v67
	v_max_f32_e32 v68, 0, v68
	v_max_f32_e32 v69, 0, v69
	v_max_f32_e32 v70, 0, v70
	v_max_f32_e32 v71, 0, v71
	v_mul_f32_e32 v76, v76, v76
	v_mul_f32_e32 v72, v72, v72
	v_mul_f32_e32 v77, v77, v77
	v_mul_f32_e32 v73, v73, v73
	v_mul_f32_e32 v78, v78, v78
	v_mul_f32_e32 v74, v74, v74
	v_mul_f32_e32 v79, v79, v79
	v_mul_f32_e32 v75, v75, v75
	v_mul_f32_e32 v82, v64, v64
	v_mul_f32_e32 v83, v65, v65
	v_mul_f32_e32 v84, v66, v66
	v_mul_f32_e32 v85, v67, v67
	v_cvt_pk_bf16_f32 v64, v76, v77
	v_cvt_pk_bf16_f32 v65, v78, v79
	v_cvt_pk_bf16_f32 v66, v72, v73
	v_cvt_pk_bf16_f32 v67, v74, v75
	v_mul_f32_e32 v68, v68, v68
	v_mul_f32_e32 v69, v69, v69
	v_mul_f32_e32 v70, v70, v70
	v_mul_f32_e32 v71, v71, v71
	global_store_dwordx4 v[80:81], v[64:67], off
	s_nop 1
	v_cvt_pk_bf16_f32 v64, v68, v69
	v_cvt_pk_bf16_f32 v65, v70, v71
	v_cvt_pk_bf16_f32 v66, v82, v83
	v_cvt_pk_bf16_f32 v67, v84, v85
	global_store_dwordx4 v[80:81], v[64:67], off offset:256
	s_waitcnt vmcnt(11)
	s_nop 0
	v_mov_b32_e32 v64, v164
	v_mov_b32_e32 v65, v165
	v_ffbh_u32_e32 v66, v65
	v_min_u32_e32 v66, 32, v66
	v_lshlrev_b64 v[64:65], v66, v[64:65]
	v_min_u32_e32 v64, 1, v64
	v_or_b32_e32 v64, v65, v64
	v_cvt_f32_u32_e32 v64, v64
	v_sub_u32_e32 v65, 32, v66
	v_ldexp_f32 v64, v64, v65
	v_fmamk_f32 v64, v64, 0x30000000, v208
	v_mul_f32_e32 v65, 0x4f800000, v64
	v_cmp_gt_f32_e32 vcc, s33, v64
	s_nop 1
	v_cndmask_b32_e32 v66, v64, v65, vcc
	v_sqrt_f32_e32 v67, v66
	v_lshl_add_u64 v[64:65], v[138:139], 0, s[4:5]
	v_add_u32_e32 v68, -1, v67
	v_add_u32_e32 v69, 1, v67
	v_fma_f32 v70, -v68, v67, v66
	v_fma_f32 v71, -v69, v67, v66
	v_cmp_ge_f32_e64 s[4:5], 0, v70
	s_nop 1
	v_cndmask_b32_e64 v67, v67, v68, s[4:5]
	v_cmp_lt_f32_e64 s[4:5], 0, v71
	s_nop 1
	v_cndmask_b32_e64 v67, v67, v69, s[4:5]
	v_mul_f32_e32 v68, 0x37800000, v67
	v_cndmask_b32_e32 v67, v67, v68, vcc
	v_cmp_class_f32_e32 vcc, v66, v209
	s_nop 1
	v_cndmask_b32_e32 v68, v67, v66, vcc
	v_div_scale_f32 v69, s[4:5], v68, v68, 1.0
	v_rcp_f32_e32 v70, v69
	s_mov_b32 s4, 0x200000
	v_add_co_u32_e32 v66, vcc, s4, v138
	v_fma_f32 v72, -v69, v70, 1.0
	s_nop 0
	v_addc_co_u32_e32 v67, vcc, 0, v139, vcc
	v_div_scale_f32 v71, vcc, 1.0, v68, 1.0
	v_fmac_f32_e32 v70, v72, v70
	v_mul_f32_e32 v72, v71, v70
	v_fma_f32 v73, -v69, v72, v71
	v_fmac_f32_e32 v72, v73, v70
	v_fma_f32 v69, -v69, v72, v71
	v_div_fmas_f32 v69, v69, v70, v72
	v_div_fixup_f32 v68, v69, v68, 1.0
	v_pk_mul_f32 v[62:63], v[62:63], v[68:69] op_sel_hi:[1,0]
	v_pk_mul_f32 v[60:61], v[60:61], v[68:69] op_sel_hi:[1,0]
	v_pk_mul_f32 v[58:59], v[58:59], v[68:69] op_sel_hi:[1,0]
	v_pk_mul_f32 v[56:57], v[56:57], v[68:69] op_sel_hi:[1,0]
	v_pk_mul_f32 v[50:51], v[50:51], v[68:69] op_sel_hi:[1,0]
	v_pk_mul_f32 v[48:49], v[48:49], v[68:69] op_sel_hi:[1,0]
	v_pk_mul_f32 v[54:55], v[54:55], v[68:69] op_sel_hi:[1,0]
	v_pk_mul_f32 v[52:53], v[52:53], v[68:69] op_sel_hi:[1,0]
	v_max_f32_e32 v60, 0, v60
	v_max_f32_e32 v56, 0, v56
	v_max_f32_e32 v61, 0, v61
	v_max_f32_e32 v57, 0, v57
	v_max_f32_e32 v62, 0, v62
	v_max_f32_e32 v58, 0, v58
	v_max_f32_e32 v63, 0, v63
	v_max_f32_e32 v59, 0, v59
	v_max_f32_e32 v48, 0, v48
	v_max_f32_e32 v49, 0, v49
	v_max_f32_e32 v50, 0, v50
	v_max_f32_e32 v51, 0, v51
	v_max_f32_e32 v52, 0, v52
	v_max_f32_e32 v53, 0, v53
	v_max_f32_e32 v54, 0, v54
	v_max_f32_e32 v55, 0, v55
	v_mul_f32_e32 v60, v60, v60
	v_mul_f32_e32 v56, v56, v56
	v_mul_f32_e32 v61, v61, v61
	v_mul_f32_e32 v57, v57, v57
	v_mul_f32_e32 v62, v62, v62
	v_mul_f32_e32 v58, v58, v58
	v_mul_f32_e32 v63, v63, v63
	v_mul_f32_e32 v59, v59, v59
	v_mul_f32_e32 v68, v48, v48
	v_mul_f32_e32 v69, v49, v49
	v_mul_f32_e32 v70, v50, v50
	v_mul_f32_e32 v71, v51, v51
	v_cvt_pk_bf16_f32 v48, v60, v61
	v_cvt_pk_bf16_f32 v49, v62, v63
	v_cvt_pk_bf16_f32 v50, v56, v57
	v_cvt_pk_bf16_f32 v51, v58, v59
	v_mul_f32_e32 v52, v52, v52
	v_mul_f32_e32 v53, v53, v53
	v_mul_f32_e32 v54, v54, v54
	v_mul_f32_e32 v55, v55, v55
	global_store_dwordx4 v[66:67], v[48:51], off
	s_mov_b64 s[4:5], 0x240000
	s_nop 0
	v_cvt_pk_bf16_f32 v48, v52, v53
	v_cvt_pk_bf16_f32 v49, v54, v55
	v_cvt_pk_bf16_f32 v50, v68, v69
	v_cvt_pk_bf16_f32 v51, v70, v71
	global_store_dwordx4 v[64:65], v[48:51], off offset:256
	s_waitcnt vmcnt(12)
; __device__ __forceinline__ unsigned cvt_pk_bf16(float lo, float hi) { unsigned r; asm volatile("v_cvt_pk_bf16_f32 %0, %1, %2" : "=v"(r) : "v"(lo), "v"(hi)); return r; }
;     __device__ __forceinline__ void operator()(const f32x4 (&acc)[2][2][4][2], const Unit& u, int wr, int wc, int fr, int fq) const {
;     ...
;             for (int m = 0; m < 4; ++m) { bf16_t* rowp = O + (size_t)(row0 + ai * HALF + m * 16) * ldc + col0;
;                 const float rs = rowss ? sc * (1.0f / sqrtf((float)__hip_atomic_load(rowss + row0 + ai * HALF + m * 16, __ATOMIC_RELAXED, __HIP_MEMORY_SCOPE_AGENT) * (1.0f / (2048.0f * 1048576.0f)) + 1e-6f)) : sc;
; #pragma unroll
;                 for (int bj = 0; bj < 2; ++bj) { f32x4 v0 = acc[ai][bj][m][0] * rs, v1 = acc[ai][bj][m][1] * rs;
;                     if (ACT == 1) {
; #pragma unroll
;                         for (int e = 0; e < 4; ++e) { float a = v0[e] > 0.f ? v0[e] : 0.f; v0[e] = a * a; float b = v1[e] > 0.f ? v1[e] : 0.f; v1[e] = b * b; } }
;                     u32x4 w; w.x = cvt_pk_bf16(v0[0], v0[1]); w.y = cvt_pk_bf16(v0[2], v0[3]); w.z = cvt_pk_bf16(v1[0], v1[1]); w.w = cvt_pk_bf16(v1[2], v1[3]);
;                     *(u32x4*)(rowp + bj * HALF) = w; } }
	s_nop 0
	v_mov_b32_e32 v48, v166
	v_mov_b32_e32 v49, v167
	v_ffbh_u32_e32 v50, v49
	v_min_u32_e32 v50, 32, v50
	v_lshlrev_b64 v[48:49], v50, v[48:49]
	v_min_u32_e32 v48, 1, v48
	v_or_b32_e32 v48, v49, v48
	v_cvt_f32_u32_e32 v48, v48
	v_sub_u32_e32 v49, 32, v50
	v_ldexp_f32 v48, v48, v49
	v_fmamk_f32 v48, v48, 0x30000000, v208
	v_mul_f32_e32 v49, 0x4f800000, v48
	v_cmp_gt_f32_e32 vcc, s33, v48
	s_nop 1
	v_cndmask_b32_e32 v50, v48, v49, vcc
	v_sqrt_f32_e32 v51, v50
	v_lshl_add_u64 v[48:49], v[138:139], 0, s[4:5]
	v_add_u32_e32 v52, -1, v51
	v_add_u32_e32 v53, 1, v51
	v_fma_f32 v54, -v52, v51, v50
	v_fma_f32 v55, -v53, v51, v50
	v_cmp_ge_f32_e64 s[4:5], 0, v54
	s_nop 1
	v_cndmask_b32_e64 v51, v51, v52, s[4:5]
	v_cmp_lt_f32_e64 s[4:5], 0, v55
	s_nop 1
	v_cndmask_b32_e64 v51, v51, v53, s[4:5]
	v_mul_f32_e32 v52, 0x37800000, v51
	v_cndmask_b32_e32 v51, v51, v52, vcc
	v_cmp_class_f32_e32 vcc, v50, v209
	s_nop 1
	v_cndmask_b32_e32 v52, v51, v50, vcc
	v_div_scale_f32 v53, s[4:5], v52, v52, 1.0
	v_rcp_f32_e32 v54, v53
	s_mov_b32 s4, 0x240000
	v_add_co_u32_e32 v50, vcc, s4, v138
	v_fma_f32 v56, -v53, v54, 1.0
	s_nop 0
	v_addc_co_u32_e32 v51, vcc, 0, v139, vcc
	v_div_scale_f32 v55, vcc, 1.0, v52, 1.0
	v_fmac_f32_e32 v54, v56, v54
	v_mul_f32_e32 v56, v55, v54
	v_fma_f32 v57, -v53, v56, v55
	v_fmac_f32_e32 v56, v57, v54
	v_fma_f32 v53, -v53, v56, v55
	v_div_fmas_f32 v53, v53, v54, v56
	v_div_fixup_f32 v52, v53, v52, 1.0
	v_pk_mul_f32 v[46:47], v[46:47], v[52:53] op_sel_hi:[1,0]
	v_pk_mul_f32 v[44:45], v[44:45], v[52:53] op_sel_hi:[1,0]
	v_pk_mul_f32 v[42:43], v[42:43], v[52:53] op_sel_hi:[1,0]
	v_pk_mul_f32 v[40:41], v[40:41], v[52:53] op_sel_hi:[1,0]
	v_pk_mul_f32 v[34:35], v[34:35], v[52:53] op_sel_hi:[1,0]
	v_pk_mul_f32 v[32:33], v[32:33], v[52:53] op_sel_hi:[1,0]
	v_pk_mul_f32 v[38:39], v[38:39], v[52:53] op_sel_hi:[1,0]
	v_pk_mul_f32 v[36:37], v[36:37], v[52:53] op_sel_hi:[1,0]
	v_max_f32_e32 v44, 0, v44
	v_max_f32_e32 v40, 0, v40
	v_max_f32_e32 v45, 0, v45
	v_max_f32_e32 v41, 0, v41
	v_max_f32_e32 v46, 0, v46
	v_max_f32_e32 v42, 0, v42
	v_max_f32_e32 v47, 0, v47
	v_max_f32_e32 v43, 0, v43
	v_max_f32_e32 v32, 0, v32
	v_max_f32_e32 v33, 0, v33
	v_max_f32_e32 v34, 0, v34
	v_max_f32_e32 v35, 0, v35
	v_max_f32_e32 v36, 0, v36
	v_max_f32_e32 v37, 0, v37
	v_max_f32_e32 v38, 0, v38
	v_max_f32_e32 v39, 0, v39
	v_mul_f32_e32 v44, v44, v44
	v_mul_f32_e32 v40, v40, v40
	v_mul_f32_e32 v45, v45, v45
	v_mul_f32_e32 v41, v41, v41
	v_mul_f32_e32 v46, v46, v46
	v_mul_f32_e32 v42, v42, v42
	v_mul_f32_e32 v47, v47, v47
	v_mul_f32_e32 v43, v43, v43
	v_mul_f32_e32 v52, v32, v32
	v_mul_f32_e32 v53, v33, v33
	v_mul_f32_e32 v54, v34, v34
	v_mul_f32_e32 v55, v35, v35
	v_cvt_pk_bf16_f32 v32, v44, v45
	v_cvt_pk_bf16_f32 v33, v46, v47
	v_cvt_pk_bf16_f32 v34, v40, v41
	v_cvt_pk_bf16_f32 v35, v42, v43
	v_mul_f32_e32 v36, v36, v36
	v_mul_f32_e32 v37, v37, v37
	v_mul_f32_e32 v38, v38, v38
	v_mul_f32_e32 v39, v39, v39
	global_store_dwordx4 v[50:51], v[32:35], off
	s_mov_b64 s[4:5], 0x280000
	s_nop 0
	v_cvt_pk_bf16_f32 v32, v36, v37
	v_cvt_pk_bf16_f32 v33, v38, v39
	v_cvt_pk_bf16_f32 v34, v52, v53
	v_cvt_pk_bf16_f32 v35, v54, v55
	global_store_dwordx4 v[48:49], v[32:35], off offset:256
	s_waitcnt vmcnt(13)
	s_nop 0
	v_mov_b32_e32 v32, v168
	v_mov_b32_e32 v33, v169
	v_ffbh_u32_e32 v34, v33
	v_min_u32_e32 v34, 32, v34
	v_lshlrev_b64 v[32:33], v34, v[32:33]
	v_min_u32_e32 v32, 1, v32
	v_or_b32_e32 v32, v33, v32
	v_cvt_f32_u32_e32 v32, v32
	v_sub_u32_e32 v33, 32, v34
	v_ldexp_f32 v32, v32, v33
	v_fmamk_f32 v32, v32, 0x30000000, v208
	v_mul_f32_e32 v33, 0x4f800000, v32
	v_cmp_gt_f32_e32 vcc, s33, v32
	s_nop 1
	v_cndmask_b32_e32 v34, v32, v33, vcc
	v_sqrt_f32_e32 v35, v34
	v_lshl_add_u64 v[32:33], v[138:139], 0, s[4:5]
	v_add_u32_e32 v36, -1, v35
	v_add_u32_e32 v37, 1, v35
	v_fma_f32 v38, -v36, v35, v34
	v_fma_f32 v39, -v37, v35, v34
	v_cmp_ge_f32_e64 s[4:5], 0, v38
	s_nop 1
	v_cndmask_b32_e64 v35, v35, v36, s[4:5]
	v_cmp_lt_f32_e64 s[4:5], 0, v39
	s_nop 1
	v_cndmask_b32_e64 v35, v35, v37, s[4:5]
	v_mul_f32_e32 v36, 0x37800000, v35
	v_cndmask_b32_e32 v35, v35, v36, vcc
	v_cmp_class_f32_e32 vcc, v34, v209
	s_nop 1
	v_cndmask_b32_e32 v36, v35, v34, vcc
	v_div_scale_f32 v37, s[4:5], v36, v36, 1.0
	v_rcp_f32_e32 v38, v37
	s_mov_b32 s4, 0x280000
	v_add_co_u32_e32 v34, vcc, s4, v138
	v_fma_f32 v40, -v37, v38, 1.0
	s_nop 0
	v_addc_co_u32_e32 v35, vcc, 0, v139, vcc
	v_div_scale_f32 v39, vcc, 1.0, v36, 1.0
	v_fmac_f32_e32 v38, v40, v38
	v_mul_f32_e32 v40, v39, v38
	v_fma_f32 v41, -v37, v40, v39
	v_fmac_f32_e32 v40, v41, v38
	v_fma_f32 v37, -v37, v40, v39
	v_div_fmas_f32 v37, v37, v38, v40
	v_div_fixup_f32 v36, v37, v36, 1.0
	v_pk_mul_f32 v[30:31], v[30:31], v[36:37] op_sel_hi:[1,0]
	v_pk_mul_f32 v[28:29], v[28:29], v[36:37] op_sel_hi:[1,0]
	v_pk_mul_f32 v[26:27], v[26:27], v[36:37] op_sel_hi:[1,0]
	v_pk_mul_f32 v[24:25], v[24:25], v[36:37] op_sel_hi:[1,0]
	v_pk_mul_f32 v[18:19], v[18:19], v[36:37] op_sel_hi:[1,0]
	v_pk_mul_f32 v[16:17], v[16:17], v[36:37] op_sel_hi:[1,0]
	v_pk_mul_f32 v[22:23], v[22:23], v[36:37] op_sel_hi:[1,0]
	v_pk_mul_f32 v[20:21], v[20:21], v[36:37] op_sel_hi:[1,0]
	v_max_f32_e32 v28, 0, v28
	v_max_f32_e32 v24, 0, v24
	v_max_f32_e32 v29, 0, v29
	v_max_f32_e32 v25, 0, v25
	v_max_f32_e32 v30, 0, v30
	v_max_f32_e32 v26, 0, v26
	v_max_f32_e32 v31, 0, v31
	v_max_f32_e32 v27, 0, v27
	v_max_f32_e32 v16, 0, v16
	v_max_f32_e32 v17, 0, v17
	v_max_f32_e32 v18, 0, v18
	v_max_f32_e32 v19, 0, v19
	v_max_f32_e32 v20, 0, v20
	v_max_f32_e32 v21, 0, v21
	v_max_f32_e32 v22, 0, v22
	v_max_f32_e32 v23, 0, v23
	v_mul_f32_e32 v28, v28, v28
	v_mul_f32_e32 v24, v24, v24
	v_mul_f32_e32 v29, v29, v29
	v_mul_f32_e32 v25, v25, v25
	v_mul_f32_e32 v30, v30, v30
	v_mul_f32_e32 v26, v26, v26
	v_mul_f32_e32 v31, v31, v31
	v_mul_f32_e32 v27, v27, v27
	v_mul_f32_e32 v36, v16, v16
	v_mul_f32_e32 v37, v17, v17
	v_mul_f32_e32 v38, v18, v18
	v_mul_f32_e32 v39, v19, v19
	v_cvt_pk_bf16_f32 v16, v28, v29
	v_cvt_pk_bf16_f32 v17, v30, v31
	v_cvt_pk_bf16_f32 v18, v24, v25
	v_cvt_pk_bf16_f32 v19, v26, v27
	v_mul_f32_e32 v20, v20, v20
	v_mul_f32_e32 v21, v21, v21
	v_mul_f32_e32 v22, v22, v22
	v_mul_f32_e32 v23, v23, v23
	global_store_dwordx4 v[34:35], v[16:19], off
	s_mov_b64 s[4:5], 0x2c0000
	s_nop 0
	v_cvt_pk_bf16_f32 v16, v20, v21
	v_cvt_pk_bf16_f32 v17, v22, v23
	v_cvt_pk_bf16_f32 v18, v36, v37
	v_cvt_pk_bf16_f32 v19, v38, v39
	global_store_dwordx4 v[32:33], v[16:19], off offset:256
	s_waitcnt vmcnt(14)
; #define PG8_WAIT_V(n) asm volatile("s_waitcnt vmcnt(" #n ")" ::: "memory")
;     __device__ __forceinline__ void operator()(const f32x4 (&acc)[2][2][4][2], const Unit& u, int wr, int wc, int fr, int fq) const {
;     ...
;             for (int m = 0; m < 4; ++m) { bf16_t* rowp = O + (size_t)(row0 + ai * HALF + m * 16) * ldc + col0;
;                 const float rs = rowss ? sc * (1.0f / sqrtf((float)__hip_atomic_load(rowss + row0 + ai * HALF + m * 16, __ATOMIC_RELAXED, __HIP_MEMORY_SCOPE_AGENT) * (1.0f / (2048.0f * 1048576.0f)) + 1e-6f)) : sc;
; #pragma unroll
;                 for (int bj = 0; bj < 2; ++bj) { f32x4 v0 = acc[ai][bj][m][0] * rs, v1 = acc[ai][bj][m][1] * rs;
;                     if (ACT == 1) {
; #pragma unroll
;                         for (int e = 0; e < 4; ++e) { float a = v0[e] > 0.f ? v0[e] : 0.f; v0[e] = a * a; float b = v1[e] > 0.f ? v1[e] : 0.f; v1[e] = b * b; } }
;                     u32x4 w; w.x = cvt_pk_bf16(v0[0], v0[1]); w.y = cvt_pk_bf16(v0[2], v0[3]); w.z = cvt_pk_bf16(v1[0], v1[1]); w.w = cvt_pk_bf16(v1[2], v1[3]);
;                     *(u32x4*)(rowp + bj * HALF) = w; } }
; template <class Epi, class Sched, bool ALIGN_EPI = false, bool SP2 = false>
; __device__ __forceinline__ void gemm_phase(PG8_LAS unsigned char* lds, const Gemm g, const Sched& S, const Epi& E, const int wid_in) {
;     ...
;     for (;;) {
;         const bool has_next = S.next(ui + 1, nxt);
;         const char* nA = has_next ? (const char*)g.A + (size_t)nxt.pm * tstep : cA; const char* nB = has_next ? (const char*)g.Bt + (size_t)nxt.pn * tstep : cB;
;         for (int t = 0; t < nt; t += 2) {
;             const bool last = (t == nt - 2);
;             const char* a1 = cA + (size_t)(t + 1) * kstep;
;             const char* a2 = last ? nA : cA + (size_t)(t + 2) * kstep; const char* b2 = last ? nB : cB + (size_t)(t + 2) * kstep;
;             const char* a3 = a2 + kstep; const char* b3 = b2 + kstep;
;             if (last && has_next) S.a_ready(nxt);
;             if constexpr (SP2) {
;             PG8_LDB(B0, 0, 0); PG8_LDB(B1, 0, 1); PG8_SCHED; PG8_LDA(At, 0, 0); PG8_STAGE(PG8_SA(1, 1), a1 + hstep, voffA);
;             PG8_WAIT_V(8); PG8_WAIT_L(0); PG8_BAR; PG8_MMA(0, 0, At, B0); PG8_MMA(0, 1, At, B1); PG8_BAR; PG8_SCHED;
;             PG8_LDA(At, 0, 1); PG8_STAGE(PG8_SB(0, 0), b2, voffB); PG8_STAGE(PG8_SB(0, 1), b2 + hstep, voffB); PG8_STAGE(PG8_SA(0, 0), a2, voffA);
	s_nop 0
	v_mov_b32_e32 v16, v170
	v_mov_b32_e32 v17, v171
	v_ffbh_u32_e32 v18, v17
	v_min_u32_e32 v18, 32, v18
	v_lshlrev_b64 v[16:17], v18, v[16:17]
	v_min_u32_e32 v16, 1, v16
	v_or_b32_e32 v16, v17, v16
	v_cvt_f32_u32_e32 v16, v16
	v_sub_u32_e32 v17, 32, v18
	v_ldexp_f32 v16, v16, v17
	v_fmamk_f32 v16, v16, 0x30000000, v208
	v_mul_f32_e32 v17, 0x4f800000, v16
	v_cmp_gt_f32_e32 vcc, s33, v16
	s_nop 1
	v_cndmask_b32_e32 v18, v16, v17, vcc
	v_sqrt_f32_e32 v19, v18
	v_lshl_add_u64 v[16:17], v[138:139], 0, s[4:5]
	v_add_u32_e32 v20, -1, v19
	v_add_u32_e32 v21, 1, v19
	v_fma_f32 v22, -v20, v19, v18
	v_fma_f32 v23, -v21, v19, v18
	v_cmp_ge_f32_e64 s[4:5], 0, v22
	s_nop 1
	v_cndmask_b32_e64 v19, v19, v20, s[4:5]
	v_cmp_lt_f32_e64 s[4:5], 0, v23
	s_nop 1
	v_cndmask_b32_e64 v19, v19, v21, s[4:5]
	v_mul_f32_e32 v20, 0x37800000, v19
	v_cndmask_b32_e32 v19, v19, v20, vcc
	v_cmp_class_f32_e32 vcc, v18, v209
	s_nop 1
	v_cndmask_b32_e32 v20, v19, v18, vcc
	v_div_scale_f32 v21, s[4:5], v20, v20, 1.0
	v_rcp_f32_e32 v22, v21
	s_mov_b32 s4, 0x2c0000
	v_add_co_u32_e32 v18, vcc, s4, v138
	v_fma_f32 v24, -v21, v22, 1.0
	s_nop 0
	v_addc_co_u32_e32 v19, vcc, 0, v139, vcc
	v_div_scale_f32 v23, vcc, 1.0, v20, 1.0
	v_fmac_f32_e32 v22, v24, v22
	v_mul_f32_e32 v24, v23, v22
	v_fma_f32 v25, -v21, v24, v23
	v_fmac_f32_e32 v24, v25, v22
	v_fma_f32 v21, -v21, v24, v23
	v_div_fmas_f32 v21, v21, v22, v24
	v_div_fixup_f32 v20, v21, v20, 1.0
	v_pk_mul_f32 v[14:15], v[14:15], v[20:21] op_sel_hi:[1,0]
	v_pk_mul_f32 v[12:13], v[12:13], v[20:21] op_sel_hi:[1,0]
	v_pk_mul_f32 v[10:11], v[10:11], v[20:21] op_sel_hi:[1,0]
	v_pk_mul_f32 v[8:9], v[8:9], v[20:21] op_sel_hi:[1,0]
	v_pk_mul_f32 v[2:3], v[2:3], v[20:21] op_sel_hi:[1,0]
	v_pk_mul_f32 v[0:1], v[0:1], v[20:21] op_sel_hi:[1,0]
	v_pk_mul_f32 v[6:7], v[6:7], v[20:21] op_sel_hi:[1,0]
	v_pk_mul_f32 v[4:5], v[4:5], v[20:21] op_sel_hi:[1,0]
	v_max_f32_e32 v12, 0, v12
	v_max_f32_e32 v8, 0, v8
	v_max_f32_e32 v13, 0, v13
	v_max_f32_e32 v9, 0, v9
	v_max_f32_e32 v14, 0, v14
	v_max_f32_e32 v10, 0, v10
	v_max_f32_e32 v15, 0, v15
	v_max_f32_e32 v11, 0, v11
	v_max_f32_e32 v0, 0, v0
	v_max_f32_e32 v1, 0, v1
	v_max_f32_e32 v2, 0, v2
	v_max_f32_e32 v3, 0, v3
	s_andn2_b64 vcc, exec, s[0:1]
	v_max_f32_e32 v4, 0, v4
	v_max_f32_e32 v5, 0, v5
	v_max_f32_e32 v6, 0, v6
	v_max_f32_e32 v7, 0, v7
	v_mul_f32_e32 v12, v12, v12
	v_mul_f32_e32 v8, v8, v8
	v_mul_f32_e32 v13, v13, v13
	v_mul_f32_e32 v9, v9, v9
	v_mul_f32_e32 v14, v14, v14
	v_mul_f32_e32 v10, v10, v10
	v_mul_f32_e32 v15, v15, v15
	v_mul_f32_e32 v11, v11, v11
	v_mul_f32_e32 v20, v0, v0
	v_mul_f32_e32 v21, v1, v1
	v_mul_f32_e32 v22, v2, v2
	v_mul_f32_e32 v23, v3, v3
	v_cvt_pk_bf16_f32 v0, v12, v13
	v_cvt_pk_bf16_f32 v1, v14, v15
	v_cvt_pk_bf16_f32 v2, v8, v9
	v_cvt_pk_bf16_f32 v3, v10, v11
	s_mov_b64 s[0:1], -1
	v_mul_f32_e32 v4, v4, v4
	v_mul_f32_e32 v5, v5, v5
	v_mul_f32_e32 v6, v6, v6
	v_mul_f32_e32 v7, v7, v7
	global_store_dwordx4 v[18:19], v[0:3], off
	s_nop 1
	v_cvt_pk_bf16_f32 v0, v4, v5
	v_cvt_pk_bf16_f32 v1, v6, v7
	v_cvt_pk_bf16_f32 v2, v20, v21
	v_cvt_pk_bf16_f32 v3, v22, v23
	global_store_dwordx4 v[16:17], v[0:3], off offset:256
	s_cbranch_vccnz .LBB0_1204
	s_andn2_b64 vcc, exec, s[6:7]
	s_cbranch_vccnz .LBB0_1203
	s_barrier
	s_branch .LBB0_1203
